# phase_up conv/SiLU epilogue: two independent rows per iteration with interleaved dependency chains and scalar loop control (per-row arithmetic unchanged)
# speedup vs baseline: 1.0056x; 1.0056x over previous
; #define WAIT_V0() asm volatile("s_waitcnt vmcnt(0)" ::: "memory")
; DI int glds_row(int i) { const int tid = ltid(); return ((tid >> 6) * 4 + i) * 8 + ((tid & 63) >> 3); }
; DI int glds_chunk(int row) { return (ltid() & 7) ^ ((row >> 1) & 7); }
; DI void gemm_core(char* smem, int nk, const char* Ab, const char* Bb, const unsigned (&aoff)[4], const unsigned (&boff)[4],
;                   f32x16 (&acc)[2][2]) {
;     ...
;   auto stage = [&](int buf, int kt) __attribute__((always_inline)) {
;     const char* ak = Ab + kt * 128;
;     const char* bk = Bb + kt * 128;
;     char* sa = smem + buf * STAGE_B + w * 4096;
; #pragma unroll
;     for (int i = 0; i < 4; ++i) {
;       __builtin_amdgcn_global_load_lds((const unsigned*)(ak + aoff[i]), (unsigned*)(sa + i * 1024), 16, 0, 0);
;       __builtin_amdgcn_global_load_lds((const unsigned*)(bk + boff[i]), (unsigned*)(sa + 16384 + i * 1024), 16, 0, 0);
;     }
;   };
;   stage(0, 0);
;   WAIT_V0();
;   __syncthreads();
; DI void phase_up(const Params& P, int layer, char* smem) {
;     ...
;   for (int t0 = blockIdx.x; t0 < MT * NT; t0 += gridDim.x) {
;     const int tl = xcd_tile(t0, MT * NT) - (t0 & 7) * ((MT * NT) >> 3);
;     const int mt = (t0 & 1) * 131 + tl / 11, nt = ((t0 & 7) >> 1) * 11 + tl % 11;
;     const int b = mt / 131, i = mt % 131;
;     const int tb0 = i * 126 - 2;
;     unsigned aoff[4], boff[4];
;     const char* Abase = (const char*)(hn + (size_t)b * S_ * 1024);
;     const unsigned zoff = (unsigned)((P.ws + OFF_ZPAGE) - Abase);
; #pragma unroll
;     for (int q = 0; q < 4; ++q) {
;       const int r = glds_row(q), ch = glds_chunk(r);
;       const int tb = tb0 + r;
;       const bool ok = (tb >= 0) && (tb < S_);
;       aoff[q] = ok ? (unsigned)((tb * 1024 + ch * 8) * 2) : zoff;
;       const int wr = (r < 64) ? (nt * 64 + r) : (DFF + nt * 64 + r - 64);
;       boff[q] = (unsigned)((wr * 1024 + ch * 8) * 2);
;     }
;     f32x16 acc[2][2];
;     gemm_core(smem, 16, Abase, (const char*)wup, aoff, boff, acc);
.LBB0_25:
	s_ashr_i32 s18, s2, 3
	s_and_b32 s19, s18, 0xffffffc0
	s_lshl_b32 s20, s18, 1
	s_bfe_u32 s21, s18, 0x10005
	s_and_b32 s20, s20, 62
	s_or_b32 s19, s21, s19
	s_or_b32 s19, s19, s20
	s_or_b32 s20, s18, 63
	s_cmpk_lt_i32 s20, 0x5a1
	s_cselect_b32 s18, s19, s18
	s_bitcmp1_b32 s2, 0
	s_mul_hi_i32 s20, s18, 0x2e8ba2e9
	s_cselect_b32 s19, 0x83, 0
	s_lshr_b32 s21, s20, 31
	s_ashr_i32 s20, s20, 1
	s_add_i32 s21, s20, s21
	s_add_i32 s20, s21, s19
	s_bfe_u32 s19, s2, 0x20001
	s_mul_i32 s21, s21, 11
	s_mul_i32 s19, s19, 11
	s_sub_i32 s18, s18, s21
	s_add_i32 s21, s18, s19
	s_mul_hi_i32 s18, s20, 0x3e88cb3d
	s_lshr_b32 s19, s18, 31
	s_ashr_i32 s18, s18, 5
	v_mov_b32_e32 v0, v161
	s_add_i32 s68, s18, s19
	s_mul_i32 s18, s68, 0x83
	v_ashrrev_i32_e32 v1, 1, v0
	v_lshrrev_b32_e32 v2, 3, v0
	v_bfe_u32 v0, v0, 3, 3
	s_movk_i32 s3, 0xffe0
	s_sub_i32 s28, s20, s18
	v_and_or_b32 v0, v1, s3, v0
	v_mov_b32_e32 v1, v161
	s_mulk_i32 s28, 0x7e
	s_ashr_i32 s69, s68, 31
	v_bfe_u32 v2, v2, 1, 2
	s_add_i32 s29, s28, -2
	s_lshl_b64 s[22:23], s[68:69], 25
	v_xor_b32_e32 v1, v2, v1
	s_add_u32 s18, s84, s22
	v_lshlrev_b32_e32 v1, 4, v1
	s_addc_u32 s19, s85, s23
	s_sub_i32 s22, 0x1b508000, s22
	s_lshl_b32 s21, s21, 6
	v_add_u32_e32 v2, s29, v0
	v_and_b32_e32 v1, 0x70, v1
	s_movk_i32 s3, 0x4000
	s_add_i32 s23, s21, 0xac0
	v_lshl_or_b32 v3, v2, 11, v1
	v_mov_b32_e32 v4, s22
	v_cmp_gt_u32_e32 vcc, s3, v2
	v_mov_b32_e32 v5, s21
	v_mov_b32_e32 v12, v161
	v_cndmask_b32_e32 v136, v4, v3, vcc
	v_mov_b32_e32 v3, s23
	v_cmp_gt_i32_e32 vcc, 64, v0
	v_lshl_add_u64 v[64:65], s[18:19], 0, v[136:137]
	s_mov_b64 s[4:5], 0x100
	v_cndmask_b32_e32 v2, v3, v5, vcc
	v_add_u32_e32 v0, v2, v0
	v_lshl_or_b32 v76, v0, 11, v1
	v_mov_b32_e32 v0, v161
	s_mov_b64 s[6:7], 0x780
	v_ashrrev_i32_e32 v1, 1, v0
	v_and_b32_e32 v1, 0xffffffe0, v1
	v_bfe_u32 v0, v0, 3, 3
	v_or3_b32 v1, v1, v0, 8
	v_mov_b32_e32 v0, v161
	v_lshrrev_b32_e32 v2, 1, v1
	v_xor_b32_e32 v0, v2, v0
	v_lshlrev_b32_e32 v0, 4, v0
	v_add_u32_e32 v2, s29, v1
	v_and_b32_e32 v6, 0x70, v0
	v_lshl_or_b32 v0, v2, 11, v6
	v_cmp_gt_u32_e32 vcc, s3, v2
	s_nop 1
	v_cndmask_b32_e32 v0, v4, v0, vcc
	v_cmp_gt_i32_e32 vcc, 64, v1
	s_nop 1
	v_cndmask_b32_e32 v2, v3, v5, vcc
	v_add_u32_e32 v1, v2, v1
	v_lshl_or_b32 v77, v1, 11, v6
	v_mov_b32_e32 v1, v161
	s_nop 0
	v_ashrrev_i32_e32 v2, 1, v1
	v_and_b32_e32 v2, 0xffffffe0, v2
	v_lshrrev_b32_e32 v6, 3, v1
	v_bfe_u32 v1, v1, 3, 3
	v_or3_b32 v1, v2, v1, 16
	v_mov_b32_e32 v2, v161
	v_bfe_u32 v6, v6, 1, 2
	v_xor_b32_e32 v2, v6, v2
	v_lshlrev_b32_e32 v2, 4, v2
	v_add_u32_e32 v6, s29, v1
	v_and_b32_e32 v7, 0x70, v2
	v_lshl_or_b32 v2, v6, 11, v7
	v_cmp_gt_u32_e32 vcc, s3, v6
	s_nop 1
	v_cndmask_b32_e32 v2, v4, v2, vcc
	v_cmp_gt_i32_e32 vcc, 64, v1
	s_nop 1
	v_cndmask_b32_e32 v6, v3, v5, vcc
	v_add_u32_e32 v1, v6, v1
	v_lshl_or_b32 v78, v1, 11, v7
	v_mov_b32_e32 v1, v161
	s_nop 0
	v_ashrrev_i32_e32 v6, 1, v1
	v_and_b32_e32 v6, 0xffffffe0, v6
	v_bfe_u32 v1, v1, 3, 3
	v_or3_b32 v1, v6, v1, 24
	v_mov_b32_e32 v6, v161
	v_lshrrev_b32_e32 v7, 1, v1
	v_xor_b32_e32 v6, v7, v6
	v_lshlrev_b32_e32 v6, 4, v6
	v_add_u32_e32 v7, s29, v1
	v_and_b32_e32 v6, 0x70, v6
	v_lshl_or_b32 v8, v7, 11, v6
	v_cmp_gt_u32_e32 vcc, s3, v7
	s_mov_b32 s3, 0x1ffffc0
	v_bfe_u32 v86, v12, 1, 3
	v_cndmask_b32_e32 v4, v4, v8, vcc
	v_cmp_gt_i32_e32 vcc, 64, v1
	v_bfe_u32 v117, v12, 5, 1
	s_nop 0
	v_cndmask_b32_e32 v3, v3, v5, vcc
	v_add_u32_e32 v1, v3, v1
	v_lshl_or_b32 v84, v1, 11, v6
	v_and_b32_e32 v1, 31, v12
	v_lshrrev_b32_e32 v5, 1, v12
	v_and_or_b32 v1, v5, s3, v1
	v_lshlrev_b32_e32 v87, 7, v1
	v_lshlrev_b32_e32 v1, 6, v12
	v_and_b32_e32 v97, 0xfffff000, v1
	v_add_u32_e32 v96, 0x4000, v97
	v_readfirstlane_b32 s84, v97
	s_mov_b32 m0, s84
	v_readfirstlane_b32 s85, v96
	v_or_b32_e32 v98, 0x400, v97
	global_load_lds_dwordx4 v136, s[18:19]
	s_mov_b32 m0, s85
	v_readfirstlane_b32 s86, v98
	v_add_u32_e32 v99, 0x4400, v97
	global_load_lds_dwordx4 v76, s[0:1]
	s_mov_b32 m0, s86
	v_readfirstlane_b32 s87, v99
	v_or_b32_e32 v100, 0x800, v97
	global_load_lds_dwordx4 v0, s[18:19]
	s_mov_b32 m0, s87
	v_readfirstlane_b32 s88, v100
	v_add_u32_e32 v101, 0x4800, v97
	v_lshrrev_b32_e32 v3, 5, v12
	global_load_lds_dwordx4 v77, s[0:1]
	s_mov_b32 m0, s88
	v_readfirstlane_b32 s89, v101
	v_or_b32_e32 v102, 0xc00, v97
	v_bitop3_b32 v3, v3, v86, 1 bitop3:0x6c
	global_load_lds_dwordx4 v2, s[18:19]
	s_mov_b32 m0, s89
	v_readfirstlane_b32 s90, v102
	v_add_u32_e32 v103, 0x4c00, v97
	v_lshlrev_b32_e32 v6, 4, v3
	v_mov_b32_e32 v1, v137
	v_mov_b32_e32 v3, v137
	global_load_lds_dwordx4 v78, s[0:1]
	v_mov_b32_e32 v5, v137
	s_mov_b32 m0, s90
	v_readfirstlane_b32 s91, v103
	v_add_u32_e32 v89, 0x8000, v97
	v_lshl_add_u64 v[66:67], s[18:19], 0, v[0:1]
	v_lshl_add_u64 v[68:69], s[18:19], 0, v[2:3]
	v_lshl_add_u64 v[70:71], s[18:19], 0, v[4:5]
	global_load_lds_dwordx4 v4, s[18:19]
	s_mov_b32 m0, s91
	v_add_u32_e32 v88, 0xc000, v97
	v_readfirstlane_b32 s18, v89
	global_load_lds_dwordx4 v84, s[0:1]
	v_lshl_add_u64 v[0:1], v[64:65], 0, s[94:95]
	s_mov_b32 m0, s18
	v_readfirstlane_b32 s19, v88
	v_add_u32_e32 v90, 0x8400, v97
	s_waitcnt vmcnt(0)
	s_waitcnt vmcnt(0) lgkmcnt(0)
	s_barrier
; #define WAIT_V0() asm volatile("s_waitcnt vmcnt(0)" ::: "memory")
; DI void gemm_core(char* smem, int nk, const char* Ab, const char* Bb, const unsigned (&aoff)[4], const unsigned (&boff)[4],
;                   f32x16 (&acc)[2][2]) {
;     ...
;   for (int kt = 0; kt < nk; ++kt) {
;     const int cur = kt & 1;
;     if (kt + 1 < nk) stage(cur ^ 1, kt + 1);
;     const char* sb = smem + cur * STAGE_B;
; #pragma unroll
;     for (int ks = 0; ks < 4; ++ks) {
;       bf16x8 af[2], bfr[2];
; #pragma unroll
;       for (int mb = 0; mb < 2; ++mb) af[mb] = *(const bf16x8*)(sb + a_base + mb * 4096 + xo[ks]);
; #pragma unroll
;       for (int nb = 0; nb < 2; ++nb) bfr[nb] = *(const bf16x8*)(sb + b_base + nb * 4096 + xo[ks]);
; #pragma unroll
;       for (int mb = 0; mb < 2; ++mb)
; #pragma unroll
;         for (int nb = 0; nb < 2; ++nb)
;           acc[mb][nb] = __builtin_amdgcn_mfma_f32_32x32x16_bf16(af[mb], bfr[nb], acc[mb][nb], 0, 0, 0);
;     }
;     WAIT_V0();
;     __syncthreads();
;   }
	global_load_lds_dwordx4 v[0:1], off
	s_mov_b32 m0, s19
	v_readfirstlane_b32 s22, v90
	v_add_u32_e32 v91, 0xc400, v97
	global_load_lds_dwordx4 v76, s[14:15]
	v_lshl_add_u64 v[0:1], v[66:67], 0, s[94:95]
	s_mov_b32 m0, s22
	v_readfirstlane_b32 s23, v91
	v_add_u32_e32 v92, 0x8800, v97
	global_load_lds_dwordx4 v[0:1], off
	s_mov_b32 m0, s23
	v_readfirstlane_b32 s29, v92
	v_add_u32_e32 v93, 0xc800, v97
	global_load_lds_dwordx4 v77, s[14:15]
	v_lshl_add_u64 v[0:1], v[68:69], 0, s[94:95]
	s_mov_b32 m0, s29
	v_readfirstlane_b32 s69, v93
	v_add_u32_e32 v94, 0x8c00, v97
	global_load_lds_dwordx4 v[0:1], off
	s_mov_b32 m0, s69
	v_readfirstlane_b32 s70, v94
	v_add_u32_e32 v95, 0xcc00, v97
	global_load_lds_dwordx4 v78, s[14:15]
	v_lshl_add_u64 v[0:1], v[70:71], 0, s[94:95]
	s_mov_b32 m0, s70
	v_readfirstlane_b32 s71, v95
	global_load_lds_dwordx4 v[0:1], off
	s_mov_b32 m0, s71
	v_or_b32_e32 v79, v87, v6
	global_load_lds_dwordx4 v84, s[14:15]
	ds_read_b128 v[0:3], v79
	v_lshlrev_b32_e32 v4, 7, v12
	v_and_b32_e32 v116, 0x2f80, v4
	v_or_b32_e32 v81, v116, v6
	ds_read_b128 v[4:7], v81 offset:16384
	ds_read_b128 v[8:11], v81 offset:20480
	s_waitcnt lgkmcnt(0)
	v_mfma_f32_32x32x16_bf16 v[48:63], v[0:3], v[4:7], 0
	s_mov_b32 m0, s84
	s_mov_b32 s3, 0xfffffc0
	v_mfma_f32_32x32x16_bf16 v[32:47], v[0:3], v[8:11], 0
	ds_read_b128 v[0:3], v79 offset:4096
	s_waitcnt lgkmcnt(0)
	v_mfma_f32_32x32x16_bf16 v[16:31], v[0:3], v[4:7], 0
	v_bitop3_b32 v4, v117, v86, 2 bitop3:0x36
	v_lshlrev_b32_e32 v82, 4, v4
	v_or_b32_e32 v80, v87, v82
	ds_read_b128 v[104:107], v80
	v_or_b32_e32 v83, v116, v82
	ds_read_b128 v[108:111], v83 offset:16384
	ds_read_b128 v[112:115], v83 offset:20480
	s_waitcnt lgkmcnt(0)
	v_mfma_f32_32x32x16_bf16 v[48:63], v[104:107], v[108:111], v[48:63]
	v_bitop3_b32 v82, v117, v86, 4 bitop3:0x36
	v_lshlrev_b32_e32 v85, 4, v82
	v_or_b32_e32 v82, v87, v85
	v_or_b32_e32 v85, v116, v85
	v_bitop3_b32 v86, v117, v86, 6 bitop3:0x36
	v_mfma_f32_32x32x16_bf16 v[32:47], v[104:107], v[112:115], v[32:47]
	ds_read_b128 v[104:107], v80 offset:4096
	v_mfma_f32_32x32x16_bf16 v[0:15], v[0:3], v[8:11], 0
	s_waitcnt lgkmcnt(0)
	v_mfma_f32_32x32x16_bf16 v[16:31], v[104:107], v[108:111], v[16:31]
	ds_read_b128 v[108:111], v85 offset:16384
	v_mfma_f32_32x32x16_bf16 v[0:15], v[104:107], v[112:115], v[0:15]
	ds_read_b128 v[104:107], v82
	ds_read_b128 v[112:115], v85 offset:20480
	s_waitcnt lgkmcnt(0)
	v_mfma_f32_32x32x16_bf16 v[48:63], v[104:107], v[108:111], v[48:63]
	v_mfma_f32_32x32x16_bf16 v[32:47], v[104:107], v[112:115], v[32:47]
	ds_read_b128 v[104:107], v82 offset:4096
	s_waitcnt lgkmcnt(0)
	v_mfma_f32_32x32x16_bf16 v[16:31], v[104:107], v[108:111], v[16:31]
	v_lshlrev_b32_e32 v108, 4, v86
	v_or_b32_e32 v86, v87, v108
	v_or_b32_e32 v87, v116, v108
	ds_read_b128 v[108:111], v87 offset:16384
	v_mfma_f32_32x32x16_bf16 v[0:15], v[104:107], v[112:115], v[0:15]
	ds_read_b128 v[104:107], v86
	ds_read_b128 v[112:115], v87 offset:20480
	s_waitcnt lgkmcnt(0)
	v_mfma_f32_32x32x16_bf16 v[48:63], v[104:107], v[108:111], v[48:63]
	v_mfma_f32_32x32x16_bf16 v[32:47], v[104:107], v[112:115], v[32:47]
	ds_read_b128 v[104:107], v86 offset:4096
	s_waitcnt vmcnt(0)
	s_waitcnt vmcnt(0) lgkmcnt(0)
	s_barrier
	v_mfma_f32_32x32x16_bf16 v[16:31], v[104:107], v[108:111], v[16:31]
	v_mfma_f32_32x32x16_bf16 v[0:15], v[104:107], v[112:115], v[0:15]
	v_lshl_add_u64 v[104:105], v[64:65], 0, s[4:5]
	global_load_lds_dwordx4 v[104:105], off
	s_mov_b32 m0, s85
	v_lshl_add_u64 v[104:105], v[66:67], 0, s[4:5]
	global_load_lds_dwordx4 v76, s[16:17]
	s_mov_b32 m0, s86
	s_nop 0
	global_load_lds_dwordx4 v[104:105], off
	s_mov_b32 m0, s87
	v_lshl_add_u64 v[104:105], v[68:69], 0, s[4:5]
	global_load_lds_dwordx4 v77, s[16:17]
	s_mov_b32 m0, s88
	s_nop 0
	global_load_lds_dwordx4 v[104:105], off
	s_mov_b32 m0, s89
	v_lshl_add_u64 v[104:105], v[70:71], 0, s[4:5]
	global_load_lds_dwordx4 v78, s[16:17]
	s_mov_b32 m0, s90
	s_mov_b64 s[4:5], 0x180
	global_load_lds_dwordx4 v[104:105], off
	s_mov_b32 m0, s91
	s_nop 0
	global_load_lds_dwordx4 v84, s[16:17]
	ds_read_b128 v[104:107], v79 offset:32768
	ds_read_b128 v[108:111], v81 offset:49152
	ds_read_b128 v[112:115], v81 offset:53248
	s_waitcnt lgkmcnt(0)
	v_mfma_f32_32x32x16_bf16 v[48:63], v[104:107], v[108:111], v[48:63]
	s_mov_b32 m0, s18
	v_mfma_f32_32x32x16_bf16 v[32:47], v[104:107], v[112:115], v[32:47]
	ds_read_b128 v[104:107], v79 offset:36864
	s_waitcnt lgkmcnt(0)
	v_mfma_f32_32x32x16_bf16 v[16:31], v[104:107], v[108:111], v[16:31]
	v_mfma_f32_32x32x16_bf16 v[0:15], v[104:107], v[112:115], v[0:15]
	ds_read_b128 v[104:107], v80 offset:32768
	ds_read_b128 v[108:111], v83 offset:49152
	ds_read_b128 v[112:115], v83 offset:53248
	s_waitcnt lgkmcnt(0)
	v_mfma_f32_32x32x16_bf16 v[48:63], v[104:107], v[108:111], v[48:63]
	v_mfma_f32_32x32x16_bf16 v[32:47], v[104:107], v[112:115], v[32:47]
	ds_read_b128 v[104:107], v80 offset:36864
	s_waitcnt lgkmcnt(0)
	v_mfma_f32_32x32x16_bf16 v[16:31], v[104:107], v[108:111], v[16:31]
	v_mfma_f32_32x32x16_bf16 v[0:15], v[104:107], v[112:115], v[0:15]
	ds_read_b128 v[104:107], v82 offset:32768
	ds_read_b128 v[108:111], v85 offset:49152
	ds_read_b128 v[112:115], v85 offset:53248
	s_waitcnt lgkmcnt(0)
	v_mfma_f32_32x32x16_bf16 v[48:63], v[104:107], v[108:111], v[48:63]
	v_mfma_f32_32x32x16_bf16 v[32:47], v[104:107], v[112:115], v[32:47]
	ds_read_b128 v[104:107], v82 offset:36864
	s_waitcnt lgkmcnt(0)
	v_mfma_f32_32x32x16_bf16 v[16:31], v[104:107], v[108:111], v[16:31]
	v_mfma_f32_32x32x16_bf16 v[0:15], v[104:107], v[112:115], v[0:15]
	ds_read_b128 v[104:107], v86 offset:32768
	ds_read_b128 v[108:111], v87 offset:49152
	ds_read_b128 v[112:115], v87 offset:53248
	s_waitcnt lgkmcnt(0)
	v_mfma_f32_32x32x16_bf16 v[48:63], v[104:107], v[108:111], v[48:63]
	v_mfma_f32_32x32x16_bf16 v[32:47], v[104:107], v[112:115], v[32:47]
	ds_read_b128 v[104:107], v86 offset:36864
	s_waitcnt vmcnt(0)
	s_waitcnt vmcnt(0) lgkmcnt(0)
	s_barrier
; #define WAIT_V0() asm volatile("s_waitcnt vmcnt(0)" ::: "memory")
; DI void gemm_core(char* smem, int nk, const char* Ab, const char* Bb, const unsigned (&aoff)[4], const unsigned (&boff)[4],
;                   f32x16 (&acc)[2][2]) {
;     ...
;   for (int kt = 0; kt < nk; ++kt) {
;     const int cur = kt & 1;
;     if (kt + 1 < nk) stage(cur ^ 1, kt + 1);
;     const char* sb = smem + cur * STAGE_B;
; #pragma unroll
;     for (int ks = 0; ks < 4; ++ks) {
;       bf16x8 af[2], bfr[2];
; #pragma unroll
;       for (int mb = 0; mb < 2; ++mb) af[mb] = *(const bf16x8*)(sb + a_base + mb * 4096 + xo[ks]);
; #pragma unroll
;       for (int nb = 0; nb < 2; ++nb) bfr[nb] = *(const bf16x8*)(sb + b_base + nb * 4096 + xo[ks]);
; #pragma unroll
;       for (int mb = 0; mb < 2; ++mb)
; #pragma unroll
;         for (int nb = 0; nb < 2; ++nb)
;           acc[mb][nb] = __builtin_amdgcn_mfma_f32_32x32x16_bf16(af[mb], bfr[nb], acc[mb][nb], 0, 0, 0);
;     }
;     WAIT_V0();
;     __syncthreads();
;   }
	v_mfma_f32_32x32x16_bf16 v[16:31], v[104:107], v[108:111], v[16:31]
	v_mfma_f32_32x32x16_bf16 v[0:15], v[104:107], v[112:115], v[0:15]
	v_lshl_add_u64 v[104:105], v[64:65], 0, s[4:5]
	global_load_lds_dwordx4 v[104:105], off
	s_mov_b32 m0, s19
	v_lshl_add_u64 v[104:105], v[66:67], 0, s[4:5]
	global_load_lds_dwordx4 v76, s[42:43]
	s_mov_b32 m0, s22
	s_nop 0
	global_load_lds_dwordx4 v[104:105], off
	s_mov_b32 m0, s23
	v_lshl_add_u64 v[104:105], v[68:69], 0, s[4:5]
	global_load_lds_dwordx4 v77, s[42:43]
	s_mov_b32 m0, s29
	s_nop 0
	global_load_lds_dwordx4 v[104:105], off
	s_mov_b32 m0, s69
	v_lshl_add_u64 v[104:105], v[70:71], 0, s[4:5]
	global_load_lds_dwordx4 v78, s[42:43]
	s_mov_b32 m0, s70
	s_mov_b64 s[4:5], 0x280
	global_load_lds_dwordx4 v[104:105], off
	s_mov_b32 m0, s71
	s_nop 0
	global_load_lds_dwordx4 v84, s[42:43]
	ds_read_b128 v[104:107], v79
	ds_read_b128 v[108:111], v81 offset:16384
	ds_read_b128 v[112:115], v81 offset:20480
	s_waitcnt lgkmcnt(0)
	v_mfma_f32_32x32x16_bf16 v[48:63], v[104:107], v[108:111], v[48:63]
	s_mov_b32 m0, s84
	v_mfma_f32_32x32x16_bf16 v[32:47], v[104:107], v[112:115], v[32:47]
	ds_read_b128 v[104:107], v79 offset:4096
	s_waitcnt lgkmcnt(0)
	v_mfma_f32_32x32x16_bf16 v[16:31], v[104:107], v[108:111], v[16:31]
	v_mfma_f32_32x32x16_bf16 v[0:15], v[104:107], v[112:115], v[0:15]
	ds_read_b128 v[104:107], v80
	ds_read_b128 v[108:111], v83 offset:16384
	ds_read_b128 v[112:115], v83 offset:20480
	s_waitcnt lgkmcnt(0)
	v_mfma_f32_32x32x16_bf16 v[48:63], v[104:107], v[108:111], v[48:63]
	v_mfma_f32_32x32x16_bf16 v[32:47], v[104:107], v[112:115], v[32:47]
	ds_read_b128 v[104:107], v80 offset:4096
	s_waitcnt lgkmcnt(0)
	v_mfma_f32_32x32x16_bf16 v[16:31], v[104:107], v[108:111], v[16:31]
	v_mfma_f32_32x32x16_bf16 v[0:15], v[104:107], v[112:115], v[0:15]
	ds_read_b128 v[104:107], v82
	ds_read_b128 v[108:111], v85 offset:16384
	ds_read_b128 v[112:115], v85 offset:20480
	s_waitcnt lgkmcnt(0)
	v_mfma_f32_32x32x16_bf16 v[48:63], v[104:107], v[108:111], v[48:63]
	v_mfma_f32_32x32x16_bf16 v[32:47], v[104:107], v[112:115], v[32:47]
	ds_read_b128 v[104:107], v82 offset:4096
	s_waitcnt lgkmcnt(0)
	v_mfma_f32_32x32x16_bf16 v[16:31], v[104:107], v[108:111], v[16:31]
	v_mfma_f32_32x32x16_bf16 v[0:15], v[104:107], v[112:115], v[0:15]
	ds_read_b128 v[104:107], v86
	ds_read_b128 v[108:111], v87 offset:16384
	ds_read_b128 v[112:115], v87 offset:20480
	s_waitcnt lgkmcnt(0)
	v_mfma_f32_32x32x16_bf16 v[48:63], v[104:107], v[108:111], v[48:63]
	v_mfma_f32_32x32x16_bf16 v[32:47], v[104:107], v[112:115], v[32:47]
	ds_read_b128 v[104:107], v86 offset:4096
	s_waitcnt vmcnt(0)
	s_waitcnt vmcnt(0) lgkmcnt(0)
	s_barrier
	v_mfma_f32_32x32x16_bf16 v[16:31], v[104:107], v[108:111], v[16:31]
	v_mfma_f32_32x32x16_bf16 v[0:15], v[104:107], v[112:115], v[0:15]
	v_lshl_add_u64 v[104:105], v[64:65], 0, s[30:31]
	global_load_lds_dwordx4 v[104:105], off
	s_mov_b32 m0, s85
	v_lshl_add_u64 v[104:105], v[66:67], 0, s[30:31]
	global_load_lds_dwordx4 v76, s[44:45]
	s_mov_b32 m0, s86
	s_nop 0
	global_load_lds_dwordx4 v[104:105], off
	s_mov_b32 m0, s87
	v_lshl_add_u64 v[104:105], v[68:69], 0, s[30:31]
	global_load_lds_dwordx4 v77, s[44:45]
	s_mov_b32 m0, s88
	s_nop 0
	global_load_lds_dwordx4 v[104:105], off
	s_mov_b32 m0, s89
	v_lshl_add_u64 v[104:105], v[70:71], 0, s[30:31]
	global_load_lds_dwordx4 v78, s[44:45]
	s_mov_b32 m0, s90
	s_nop 0
	global_load_lds_dwordx4 v[104:105], off
	s_mov_b32 m0, s91
	s_nop 0
	global_load_lds_dwordx4 v84, s[44:45]
	ds_read_b128 v[104:107], v79 offset:32768
	ds_read_b128 v[108:111], v81 offset:49152
	ds_read_b128 v[112:115], v81 offset:53248
	s_waitcnt lgkmcnt(0)
	v_mfma_f32_32x32x16_bf16 v[48:63], v[104:107], v[108:111], v[48:63]
	s_mov_b32 m0, s18
	v_mfma_f32_32x32x16_bf16 v[32:47], v[104:107], v[112:115], v[32:47]
	ds_read_b128 v[104:107], v79 offset:36864
	s_waitcnt lgkmcnt(0)
	v_mfma_f32_32x32x16_bf16 v[16:31], v[104:107], v[108:111], v[16:31]
	v_mfma_f32_32x32x16_bf16 v[0:15], v[104:107], v[112:115], v[0:15]
	ds_read_b128 v[104:107], v80 offset:32768
	ds_read_b128 v[108:111], v83 offset:49152
	ds_read_b128 v[112:115], v83 offset:53248
	s_waitcnt lgkmcnt(0)
	v_mfma_f32_32x32x16_bf16 v[48:63], v[104:107], v[108:111], v[48:63]
	v_mfma_f32_32x32x16_bf16 v[32:47], v[104:107], v[112:115], v[32:47]
	ds_read_b128 v[104:107], v80 offset:36864
	s_waitcnt lgkmcnt(0)
	v_mfma_f32_32x32x16_bf16 v[16:31], v[104:107], v[108:111], v[16:31]
	v_mfma_f32_32x32x16_bf16 v[0:15], v[104:107], v[112:115], v[0:15]
	ds_read_b128 v[104:107], v82 offset:32768
	ds_read_b128 v[108:111], v85 offset:49152
	ds_read_b128 v[112:115], v85 offset:53248
	s_waitcnt lgkmcnt(0)
	v_mfma_f32_32x32x16_bf16 v[48:63], v[104:107], v[108:111], v[48:63]
	v_mfma_f32_32x32x16_bf16 v[32:47], v[104:107], v[112:115], v[32:47]
	ds_read_b128 v[104:107], v82 offset:36864
	s_waitcnt lgkmcnt(0)
	v_mfma_f32_32x32x16_bf16 v[16:31], v[104:107], v[108:111], v[16:31]
	v_mfma_f32_32x32x16_bf16 v[0:15], v[104:107], v[112:115], v[0:15]
	ds_read_b128 v[104:107], v86 offset:32768
	ds_read_b128 v[108:111], v87 offset:49152
	ds_read_b128 v[112:115], v87 offset:53248
	s_waitcnt lgkmcnt(0)
	v_mfma_f32_32x32x16_bf16 v[48:63], v[104:107], v[108:111], v[48:63]
	v_mfma_f32_32x32x16_bf16 v[32:47], v[104:107], v[112:115], v[32:47]
	ds_read_b128 v[104:107], v86 offset:36864
	s_waitcnt vmcnt(0)
	s_waitcnt vmcnt(0) lgkmcnt(0)
	s_barrier
; #define WAIT_V0() asm volatile("s_waitcnt vmcnt(0)" ::: "memory")
; DI void gemm_core(char* smem, int nk, const char* Ab, const char* Bb, const unsigned (&aoff)[4], const unsigned (&boff)[4],
;                   f32x16 (&acc)[2][2]) {
;     ...
;   for (int kt = 0; kt < nk; ++kt) {
;     const int cur = kt & 1;
;     if (kt + 1 < nk) stage(cur ^ 1, kt + 1);
;     const char* sb = smem + cur * STAGE_B;
; #pragma unroll
;     for (int ks = 0; ks < 4; ++ks) {
;       bf16x8 af[2], bfr[2];
; #pragma unroll
;       for (int mb = 0; mb < 2; ++mb) af[mb] = *(const bf16x8*)(sb + a_base + mb * 4096 + xo[ks]);
; #pragma unroll
;       for (int nb = 0; nb < 2; ++nb) bfr[nb] = *(const bf16x8*)(sb + b_base + nb * 4096 + xo[ks]);
; #pragma unroll
;       for (int mb = 0; mb < 2; ++mb)
; #pragma unroll
;         for (int nb = 0; nb < 2; ++nb)
;           acc[mb][nb] = __builtin_amdgcn_mfma_f32_32x32x16_bf16(af[mb], bfr[nb], acc[mb][nb], 0, 0, 0);
;     }
;     WAIT_V0();
;     __syncthreads();
;   }
	v_mfma_f32_32x32x16_bf16 v[16:31], v[104:107], v[108:111], v[16:31]
	v_mfma_f32_32x32x16_bf16 v[0:15], v[104:107], v[112:115], v[0:15]
	v_lshl_add_u64 v[104:105], v[64:65], 0, s[4:5]
	global_load_lds_dwordx4 v[104:105], off
	s_mov_b32 m0, s19
	v_lshl_add_u64 v[104:105], v[66:67], 0, s[4:5]
	global_load_lds_dwordx4 v76, s[46:47]
	s_mov_b32 m0, s22
	s_nop 0
	global_load_lds_dwordx4 v[104:105], off
	s_mov_b32 m0, s23
	v_lshl_add_u64 v[104:105], v[68:69], 0, s[4:5]
	global_load_lds_dwordx4 v77, s[46:47]
	s_mov_b32 m0, s29
	s_nop 0
	global_load_lds_dwordx4 v[104:105], off
	s_mov_b32 m0, s69
	v_lshl_add_u64 v[104:105], v[70:71], 0, s[4:5]
	global_load_lds_dwordx4 v78, s[46:47]
	s_mov_b32 m0, s70
	s_mov_b64 s[4:5], 0x300
	global_load_lds_dwordx4 v[104:105], off
	s_mov_b32 m0, s71
	s_nop 0
	global_load_lds_dwordx4 v84, s[46:47]
	ds_read_b128 v[104:107], v79
	ds_read_b128 v[108:111], v81 offset:16384
	ds_read_b128 v[112:115], v81 offset:20480
	s_waitcnt lgkmcnt(0)
	v_mfma_f32_32x32x16_bf16 v[48:63], v[104:107], v[108:111], v[48:63]
	s_mov_b32 m0, s84
	v_mfma_f32_32x32x16_bf16 v[32:47], v[104:107], v[112:115], v[32:47]
	ds_read_b128 v[104:107], v79 offset:4096
	s_waitcnt lgkmcnt(0)
	v_mfma_f32_32x32x16_bf16 v[16:31], v[104:107], v[108:111], v[16:31]
	v_mfma_f32_32x32x16_bf16 v[0:15], v[104:107], v[112:115], v[0:15]
	ds_read_b128 v[104:107], v80
	ds_read_b128 v[108:111], v83 offset:16384
	ds_read_b128 v[112:115], v83 offset:20480
	s_waitcnt lgkmcnt(0)
	v_mfma_f32_32x32x16_bf16 v[48:63], v[104:107], v[108:111], v[48:63]
	v_mfma_f32_32x32x16_bf16 v[32:47], v[104:107], v[112:115], v[32:47]
	ds_read_b128 v[104:107], v80 offset:4096
	s_waitcnt lgkmcnt(0)
	v_mfma_f32_32x32x16_bf16 v[16:31], v[104:107], v[108:111], v[16:31]
	v_mfma_f32_32x32x16_bf16 v[0:15], v[104:107], v[112:115], v[0:15]
	ds_read_b128 v[104:107], v82
	ds_read_b128 v[108:111], v85 offset:16384
	ds_read_b128 v[112:115], v85 offset:20480
	s_waitcnt lgkmcnt(0)
	v_mfma_f32_32x32x16_bf16 v[48:63], v[104:107], v[108:111], v[48:63]
	v_mfma_f32_32x32x16_bf16 v[32:47], v[104:107], v[112:115], v[32:47]
	ds_read_b128 v[104:107], v82 offset:4096
	s_waitcnt lgkmcnt(0)
	v_mfma_f32_32x32x16_bf16 v[16:31], v[104:107], v[108:111], v[16:31]
	v_mfma_f32_32x32x16_bf16 v[0:15], v[104:107], v[112:115], v[0:15]
	ds_read_b128 v[104:107], v86
	ds_read_b128 v[108:111], v87 offset:16384
	ds_read_b128 v[112:115], v87 offset:20480
	s_waitcnt lgkmcnt(0)
	v_mfma_f32_32x32x16_bf16 v[48:63], v[104:107], v[108:111], v[48:63]
	v_mfma_f32_32x32x16_bf16 v[32:47], v[104:107], v[112:115], v[32:47]
	ds_read_b128 v[104:107], v86 offset:4096
	s_waitcnt vmcnt(0)
	s_waitcnt vmcnt(0) lgkmcnt(0)
	s_barrier
	v_mfma_f32_32x32x16_bf16 v[16:31], v[104:107], v[108:111], v[16:31]
	v_mfma_f32_32x32x16_bf16 v[0:15], v[104:107], v[112:115], v[0:15]
	v_lshl_add_u64 v[104:105], v[64:65], 0, s[4:5]
	global_load_lds_dwordx4 v[104:105], off
	s_mov_b32 m0, s85
	v_lshl_add_u64 v[104:105], v[66:67], 0, s[4:5]
	global_load_lds_dwordx4 v76, s[48:49]
	s_mov_b32 m0, s86
	s_nop 0
	global_load_lds_dwordx4 v[104:105], off
	s_mov_b32 m0, s87
	v_lshl_add_u64 v[104:105], v[68:69], 0, s[4:5]
	global_load_lds_dwordx4 v77, s[48:49]
	s_mov_b32 m0, s88
	s_nop 0
	global_load_lds_dwordx4 v[104:105], off
	s_mov_b32 m0, s89
	v_lshl_add_u64 v[104:105], v[70:71], 0, s[4:5]
	global_load_lds_dwordx4 v78, s[48:49]
	s_mov_b32 m0, s90
	s_mov_b64 s[4:5], 0x380
	global_load_lds_dwordx4 v[104:105], off
	s_mov_b32 m0, s91
	s_nop 0
	global_load_lds_dwordx4 v84, s[48:49]
	ds_read_b128 v[104:107], v79 offset:32768
	ds_read_b128 v[108:111], v81 offset:49152
	ds_read_b128 v[112:115], v81 offset:53248
	s_waitcnt lgkmcnt(0)
	v_mfma_f32_32x32x16_bf16 v[48:63], v[104:107], v[108:111], v[48:63]
	s_mov_b32 m0, s18
	v_mfma_f32_32x32x16_bf16 v[32:47], v[104:107], v[112:115], v[32:47]
	ds_read_b128 v[104:107], v79 offset:36864
	s_waitcnt lgkmcnt(0)
	v_mfma_f32_32x32x16_bf16 v[16:31], v[104:107], v[108:111], v[16:31]
	v_mfma_f32_32x32x16_bf16 v[0:15], v[104:107], v[112:115], v[0:15]
	ds_read_b128 v[104:107], v80 offset:32768
	ds_read_b128 v[108:111], v83 offset:49152
	ds_read_b128 v[112:115], v83 offset:53248
	s_waitcnt lgkmcnt(0)
	v_mfma_f32_32x32x16_bf16 v[48:63], v[104:107], v[108:111], v[48:63]
	v_mfma_f32_32x32x16_bf16 v[32:47], v[104:107], v[112:115], v[32:47]
	ds_read_b128 v[104:107], v80 offset:36864
	s_waitcnt lgkmcnt(0)
	v_mfma_f32_32x32x16_bf16 v[16:31], v[104:107], v[108:111], v[16:31]
	v_mfma_f32_32x32x16_bf16 v[0:15], v[104:107], v[112:115], v[0:15]
	ds_read_b128 v[104:107], v82 offset:32768
	ds_read_b128 v[108:111], v85 offset:49152
	ds_read_b128 v[112:115], v85 offset:53248
	s_waitcnt lgkmcnt(0)
	v_mfma_f32_32x32x16_bf16 v[48:63], v[104:107], v[108:111], v[48:63]
	v_mfma_f32_32x32x16_bf16 v[32:47], v[104:107], v[112:115], v[32:47]
	ds_read_b128 v[104:107], v82 offset:36864
	s_waitcnt lgkmcnt(0)
	v_mfma_f32_32x32x16_bf16 v[16:31], v[104:107], v[108:111], v[16:31]
	v_mfma_f32_32x32x16_bf16 v[0:15], v[104:107], v[112:115], v[0:15]
	ds_read_b128 v[104:107], v86 offset:32768
	ds_read_b128 v[108:111], v87 offset:49152
	ds_read_b128 v[112:115], v87 offset:53248
	s_waitcnt lgkmcnt(0)
	v_mfma_f32_32x32x16_bf16 v[48:63], v[104:107], v[108:111], v[48:63]
	v_mfma_f32_32x32x16_bf16 v[32:47], v[104:107], v[112:115], v[32:47]
	ds_read_b128 v[104:107], v86 offset:36864
	s_waitcnt vmcnt(0)
	s_waitcnt vmcnt(0) lgkmcnt(0)
	s_barrier
; #define WAIT_V0() asm volatile("s_waitcnt vmcnt(0)" ::: "memory")
; DI void gemm_core(char* smem, int nk, const char* Ab, const char* Bb, const unsigned (&aoff)[4], const unsigned (&boff)[4],
;                   f32x16 (&acc)[2][2]) {
;     ...
;   for (int kt = 0; kt < nk; ++kt) {
;     const int cur = kt & 1;
;     if (kt + 1 < nk) stage(cur ^ 1, kt + 1);
;     const char* sb = smem + cur * STAGE_B;
; #pragma unroll
;     for (int ks = 0; ks < 4; ++ks) {
;       bf16x8 af[2], bfr[2];
; #pragma unroll
;       for (int mb = 0; mb < 2; ++mb) af[mb] = *(const bf16x8*)(sb + a_base + mb * 4096 + xo[ks]);
; #pragma unroll
;       for (int nb = 0; nb < 2; ++nb) bfr[nb] = *(const bf16x8*)(sb + b_base + nb * 4096 + xo[ks]);
; #pragma unroll
;       for (int mb = 0; mb < 2; ++mb)
; #pragma unroll
;         for (int nb = 0; nb < 2; ++nb)
;           acc[mb][nb] = __builtin_amdgcn_mfma_f32_32x32x16_bf16(af[mb], bfr[nb], acc[mb][nb], 0, 0, 0);
;     }
;     WAIT_V0();
;     __syncthreads();
;   }
	v_mfma_f32_32x32x16_bf16 v[16:31], v[104:107], v[108:111], v[16:31]
	v_mfma_f32_32x32x16_bf16 v[0:15], v[104:107], v[112:115], v[0:15]
	v_lshl_add_u64 v[104:105], v[64:65], 0, s[4:5]
	global_load_lds_dwordx4 v[104:105], off
	s_mov_b32 m0, s19
	v_lshl_add_u64 v[104:105], v[66:67], 0, s[4:5]
	global_load_lds_dwordx4 v76, s[50:51]
	s_mov_b32 m0, s22
	s_nop 0
	global_load_lds_dwordx4 v[104:105], off
	s_mov_b32 m0, s23
	v_lshl_add_u64 v[104:105], v[68:69], 0, s[4:5]
	global_load_lds_dwordx4 v77, s[50:51]
	s_mov_b32 m0, s29
	s_nop 0
	global_load_lds_dwordx4 v[104:105], off
	s_mov_b32 m0, s69
	v_lshl_add_u64 v[104:105], v[70:71], 0, s[4:5]
	global_load_lds_dwordx4 v78, s[50:51]
	s_mov_b32 m0, s70
	s_mov_b64 s[4:5], 0x400
	global_load_lds_dwordx4 v[104:105], off
	s_mov_b32 m0, s71
	s_nop 0
	global_load_lds_dwordx4 v84, s[50:51]
	ds_read_b128 v[104:107], v79
	ds_read_b128 v[108:111], v81 offset:16384
	ds_read_b128 v[112:115], v81 offset:20480
	s_waitcnt lgkmcnt(0)
	v_mfma_f32_32x32x16_bf16 v[48:63], v[104:107], v[108:111], v[48:63]
	s_mov_b32 m0, s84
	v_readfirstlane_b32 s84, v89
	v_mfma_f32_32x32x16_bf16 v[32:47], v[104:107], v[112:115], v[32:47]
	ds_read_b128 v[104:107], v79 offset:4096
	s_waitcnt lgkmcnt(0)
	v_mfma_f32_32x32x16_bf16 v[16:31], v[104:107], v[108:111], v[16:31]
	v_mfma_f32_32x32x16_bf16 v[0:15], v[104:107], v[112:115], v[0:15]
	ds_read_b128 v[104:107], v80
	ds_read_b128 v[108:111], v83 offset:16384
	ds_read_b128 v[112:115], v83 offset:20480
	s_waitcnt lgkmcnt(0)
	v_mfma_f32_32x32x16_bf16 v[48:63], v[104:107], v[108:111], v[48:63]
	v_mfma_f32_32x32x16_bf16 v[32:47], v[104:107], v[112:115], v[32:47]
	ds_read_b128 v[104:107], v80 offset:4096
	s_waitcnt lgkmcnt(0)
	v_mfma_f32_32x32x16_bf16 v[16:31], v[104:107], v[108:111], v[16:31]
	v_mfma_f32_32x32x16_bf16 v[0:15], v[104:107], v[112:115], v[0:15]
	ds_read_b128 v[104:107], v82
	ds_read_b128 v[108:111], v85 offset:16384
	ds_read_b128 v[112:115], v85 offset:20480
	s_waitcnt lgkmcnt(0)
	v_mfma_f32_32x32x16_bf16 v[48:63], v[104:107], v[108:111], v[48:63]
	v_mfma_f32_32x32x16_bf16 v[32:47], v[104:107], v[112:115], v[32:47]
	ds_read_b128 v[104:107], v82 offset:4096
	s_waitcnt lgkmcnt(0)
	v_mfma_f32_32x32x16_bf16 v[16:31], v[104:107], v[108:111], v[16:31]
	v_mfma_f32_32x32x16_bf16 v[0:15], v[104:107], v[112:115], v[0:15]
	ds_read_b128 v[104:107], v86
	ds_read_b128 v[108:111], v87 offset:16384
	ds_read_b128 v[112:115], v87 offset:20480
	s_waitcnt lgkmcnt(0)
	v_mfma_f32_32x32x16_bf16 v[48:63], v[104:107], v[108:111], v[48:63]
	v_mfma_f32_32x32x16_bf16 v[32:47], v[104:107], v[112:115], v[32:47]
	ds_read_b128 v[104:107], v86 offset:4096
	s_waitcnt vmcnt(0)
	s_waitcnt vmcnt(0) lgkmcnt(0)
	s_barrier
	v_mfma_f32_32x32x16_bf16 v[16:31], v[104:107], v[108:111], v[16:31]
	v_mfma_f32_32x32x16_bf16 v[0:15], v[104:107], v[112:115], v[0:15]
	v_lshl_add_u64 v[104:105], v[64:65], 0, s[4:5]
	global_load_lds_dwordx4 v[104:105], off
	s_mov_b32 m0, s85
	v_lshl_add_u64 v[104:105], v[66:67], 0, s[4:5]
	global_load_lds_dwordx4 v76, s[52:53]
	s_mov_b32 m0, s86
	v_readfirstlane_b32 s85, v88
	global_load_lds_dwordx4 v[104:105], off
	s_mov_b32 m0, s87
	v_lshl_add_u64 v[104:105], v[68:69], 0, s[4:5]
	global_load_lds_dwordx4 v77, s[52:53]
	s_mov_b32 m0, s88
	v_readfirstlane_b32 s86, v90
	global_load_lds_dwordx4 v[104:105], off
	s_mov_b32 m0, s89
	v_lshl_add_u64 v[104:105], v[70:71], 0, s[4:5]
	global_load_lds_dwordx4 v78, s[52:53]
	s_mov_b32 m0, s90
	s_mov_b64 s[4:5], 0x480
	global_load_lds_dwordx4 v[104:105], off
	s_mov_b32 m0, s91
	v_readfirstlane_b32 s87, v91
	global_load_lds_dwordx4 v84, s[52:53]
	ds_read_b128 v[104:107], v79 offset:32768
	ds_read_b128 v[108:111], v81 offset:49152
	ds_read_b128 v[112:115], v81 offset:53248
	s_waitcnt lgkmcnt(0)
	v_mfma_f32_32x32x16_bf16 v[48:63], v[104:107], v[108:111], v[48:63]
	s_mov_b32 m0, s18
	v_readfirstlane_b32 s18, v97
	v_readfirstlane_b32 s88, v92
	v_readfirstlane_b32 s89, v93
	v_readfirstlane_b32 s90, v94
	v_readfirstlane_b32 s91, v95
	v_mfma_f32_32x32x16_bf16 v[32:47], v[104:107], v[112:115], v[32:47]
	ds_read_b128 v[104:107], v79 offset:36864
	s_waitcnt lgkmcnt(0)
	v_mfma_f32_32x32x16_bf16 v[16:31], v[104:107], v[108:111], v[16:31]
	v_mfma_f32_32x32x16_bf16 v[0:15], v[104:107], v[112:115], v[0:15]
	ds_read_b128 v[104:107], v80 offset:32768
	ds_read_b128 v[108:111], v83 offset:49152
	ds_read_b128 v[112:115], v83 offset:53248
	s_waitcnt lgkmcnt(0)
	v_mfma_f32_32x32x16_bf16 v[48:63], v[104:107], v[108:111], v[48:63]
	v_mfma_f32_32x32x16_bf16 v[32:47], v[104:107], v[112:115], v[32:47]
	ds_read_b128 v[104:107], v80 offset:36864
	s_waitcnt lgkmcnt(0)
	v_mfma_f32_32x32x16_bf16 v[16:31], v[104:107], v[108:111], v[16:31]
	v_mfma_f32_32x32x16_bf16 v[0:15], v[104:107], v[112:115], v[0:15]
	ds_read_b128 v[104:107], v82 offset:32768
	ds_read_b128 v[108:111], v85 offset:49152
	ds_read_b128 v[112:115], v85 offset:53248
	s_waitcnt lgkmcnt(0)
	v_mfma_f32_32x32x16_bf16 v[48:63], v[104:107], v[108:111], v[48:63]
	v_mfma_f32_32x32x16_bf16 v[32:47], v[104:107], v[112:115], v[32:47]
	ds_read_b128 v[104:107], v82 offset:36864
	s_waitcnt lgkmcnt(0)
	v_mfma_f32_32x32x16_bf16 v[16:31], v[104:107], v[108:111], v[16:31]
	v_mfma_f32_32x32x16_bf16 v[0:15], v[104:107], v[112:115], v[0:15]
	ds_read_b128 v[104:107], v86 offset:32768
	ds_read_b128 v[108:111], v87 offset:49152
	ds_read_b128 v[112:115], v87 offset:53248
	s_waitcnt lgkmcnt(0)
	v_mfma_f32_32x32x16_bf16 v[48:63], v[104:107], v[108:111], v[48:63]
	v_mfma_f32_32x32x16_bf16 v[32:47], v[104:107], v[112:115], v[32:47]
	ds_read_b128 v[104:107], v86 offset:36864
	s_waitcnt vmcnt(0)
	s_waitcnt vmcnt(0) lgkmcnt(0)
	s_barrier
; #define WAIT_V0() asm volatile("s_waitcnt vmcnt(0)" ::: "memory")
; DI void gemm_core(char* smem, int nk, const char* Ab, const char* Bb, const unsigned (&aoff)[4], const unsigned (&boff)[4],
;                   f32x16 (&acc)[2][2]) {
;     ...
;   for (int kt = 0; kt < nk; ++kt) {
;     const int cur = kt & 1;
;     if (kt + 1 < nk) stage(cur ^ 1, kt + 1);
;     const char* sb = smem + cur * STAGE_B;
; #pragma unroll
;     for (int ks = 0; ks < 4; ++ks) {
;       bf16x8 af[2], bfr[2];
; #pragma unroll
;       for (int mb = 0; mb < 2; ++mb) af[mb] = *(const bf16x8*)(sb + a_base + mb * 4096 + xo[ks]);
; #pragma unroll
;       for (int nb = 0; nb < 2; ++nb) bfr[nb] = *(const bf16x8*)(sb + b_base + nb * 4096 + xo[ks]);
; #pragma unroll
;       for (int mb = 0; mb < 2; ++mb)
; #pragma unroll
;         for (int nb = 0; nb < 2; ++nb)
;           acc[mb][nb] = __builtin_amdgcn_mfma_f32_32x32x16_bf16(af[mb], bfr[nb], acc[mb][nb], 0, 0, 0);
;     }
;     WAIT_V0();
;     __syncthreads();
;   }
	v_mfma_f32_32x32x16_bf16 v[16:31], v[104:107], v[108:111], v[16:31]
	v_mfma_f32_32x32x16_bf16 v[0:15], v[104:107], v[112:115], v[0:15]
	v_lshl_add_u64 v[104:105], v[64:65], 0, s[4:5]
	global_load_lds_dwordx4 v[104:105], off
	s_mov_b32 m0, s19
	v_lshl_add_u64 v[104:105], v[66:67], 0, s[4:5]
	global_load_lds_dwordx4 v76, s[54:55]
	s_mov_b32 m0, s22
	v_readfirstlane_b32 s19, v96
	global_load_lds_dwordx4 v[104:105], off
	s_mov_b32 m0, s23
	v_lshl_add_u64 v[104:105], v[68:69], 0, s[4:5]
	global_load_lds_dwordx4 v77, s[54:55]
	s_mov_b32 m0, s29
	v_readfirstlane_b32 s22, v98
	global_load_lds_dwordx4 v[104:105], off
	s_mov_b32 m0, s69
	v_lshl_add_u64 v[104:105], v[70:71], 0, s[4:5]
	global_load_lds_dwordx4 v78, s[54:55]
	s_mov_b32 m0, s70
	s_mov_b64 s[4:5], 0x500
	global_load_lds_dwordx4 v[104:105], off
	s_mov_b32 m0, s71
	v_lshl_add_u64 v[96:97], v[66:67], 0, s[4:5]
	global_load_lds_dwordx4 v84, s[54:55]
	ds_read_b128 v[104:107], v79
	ds_read_b128 v[108:111], v81 offset:16384
	ds_read_b128 v[112:115], v81 offset:20480
	s_waitcnt lgkmcnt(0)
	v_mfma_f32_32x32x16_bf16 v[48:63], v[104:107], v[108:111], v[48:63]
	s_mov_b32 m0, s18
	v_readfirstlane_b32 s23, v99
	v_readfirstlane_b32 s29, v100
	v_readfirstlane_b32 s69, v101
	v_readfirstlane_b32 s70, v102
	v_readfirstlane_b32 s71, v103
	v_mfma_f32_32x32x16_bf16 v[32:47], v[104:107], v[112:115], v[32:47]
	ds_read_b128 v[104:107], v79 offset:4096
	s_waitcnt lgkmcnt(0)
	v_mfma_f32_32x32x16_bf16 v[16:31], v[104:107], v[108:111], v[16:31]
	v_mfma_f32_32x32x16_bf16 v[0:15], v[104:107], v[112:115], v[0:15]
	ds_read_b128 v[104:107], v80
	ds_read_b128 v[108:111], v83 offset:16384
	ds_read_b128 v[112:115], v83 offset:20480
	s_waitcnt lgkmcnt(0)
	v_mfma_f32_32x32x16_bf16 v[48:63], v[104:107], v[108:111], v[48:63]
	v_mfma_f32_32x32x16_bf16 v[32:47], v[104:107], v[112:115], v[32:47]
	ds_read_b128 v[104:107], v80 offset:4096
	s_waitcnt lgkmcnt(0)
	v_mfma_f32_32x32x16_bf16 v[16:31], v[104:107], v[108:111], v[16:31]
	v_mfma_f32_32x32x16_bf16 v[0:15], v[104:107], v[112:115], v[0:15]
	ds_read_b128 v[104:107], v82
	ds_read_b128 v[108:111], v85 offset:16384
	ds_read_b128 v[112:115], v85 offset:20480
	s_waitcnt lgkmcnt(0)
	v_mfma_f32_32x32x16_bf16 v[48:63], v[104:107], v[108:111], v[48:63]
	v_mfma_f32_32x32x16_bf16 v[32:47], v[104:107], v[112:115], v[32:47]
	ds_read_b128 v[104:107], v82 offset:4096
	s_waitcnt lgkmcnt(0)
	v_mfma_f32_32x32x16_bf16 v[16:31], v[104:107], v[108:111], v[16:31]
	v_mfma_f32_32x32x16_bf16 v[0:15], v[104:107], v[112:115], v[0:15]
	ds_read_b128 v[104:107], v86
	ds_read_b128 v[108:111], v87 offset:16384
	ds_read_b128 v[112:115], v87 offset:20480
	s_waitcnt lgkmcnt(0)
	v_mfma_f32_32x32x16_bf16 v[48:63], v[104:107], v[108:111], v[48:63]
	v_mfma_f32_32x32x16_bf16 v[32:47], v[104:107], v[112:115], v[32:47]
	ds_read_b128 v[104:107], v86 offset:4096
	s_waitcnt vmcnt(0)
	s_waitcnt vmcnt(0) lgkmcnt(0)
	s_barrier
	v_mfma_f32_32x32x16_bf16 v[16:31], v[104:107], v[108:111], v[16:31]
	v_mfma_f32_32x32x16_bf16 v[0:15], v[104:107], v[112:115], v[0:15]
	v_lshl_add_u64 v[104:105], v[64:65], 0, s[4:5]
	global_load_lds_dwordx4 v[104:105], off
	s_mov_b32 m0, s19
	s_nop 0
	global_load_lds_dwordx4 v76, s[56:57]
	s_mov_b32 m0, s22
	s_nop 0
	global_load_lds_dwordx4 v[96:97], off
	s_mov_b32 m0, s23
	v_lshl_add_u64 v[96:97], v[68:69], 0, s[4:5]
	global_load_lds_dwordx4 v77, s[56:57]
	s_mov_b32 m0, s29
	s_nop 0
	global_load_lds_dwordx4 v[96:97], off
	s_mov_b32 m0, s69
	v_lshl_add_u64 v[96:97], v[70:71], 0, s[4:5]
	global_load_lds_dwordx4 v78, s[56:57]
	s_mov_b32 m0, s70
	s_mov_b64 s[4:5], 0x580
	global_load_lds_dwordx4 v[96:97], off
	s_mov_b32 m0, s71
	v_lshl_add_u64 v[88:89], v[66:67], 0, s[4:5]
	global_load_lds_dwordx4 v84, s[56:57]
	ds_read_b128 v[96:99], v79 offset:32768
	ds_read_b128 v[100:103], v81 offset:49152
	ds_read_b128 v[104:107], v81 offset:53248
	s_waitcnt lgkmcnt(0)
	v_mfma_f32_32x32x16_bf16 v[48:63], v[96:99], v[100:103], v[48:63]
	s_mov_b32 m0, s84
	v_mfma_f32_32x32x16_bf16 v[32:47], v[96:99], v[104:107], v[32:47]
	ds_read_b128 v[96:99], v79 offset:36864
	s_waitcnt lgkmcnt(0)
	v_mfma_f32_32x32x16_bf16 v[16:31], v[96:99], v[100:103], v[16:31]
	v_mfma_f32_32x32x16_bf16 v[0:15], v[96:99], v[104:107], v[0:15]
	ds_read_b128 v[96:99], v80 offset:32768
	ds_read_b128 v[100:103], v83 offset:49152
	ds_read_b128 v[104:107], v83 offset:53248
	s_waitcnt lgkmcnt(0)
	v_mfma_f32_32x32x16_bf16 v[48:63], v[96:99], v[100:103], v[48:63]
	v_mfma_f32_32x32x16_bf16 v[32:47], v[96:99], v[104:107], v[32:47]
	ds_read_b128 v[96:99], v80 offset:36864
	s_waitcnt lgkmcnt(0)
	v_mfma_f32_32x32x16_bf16 v[16:31], v[96:99], v[100:103], v[16:31]
	v_mfma_f32_32x32x16_bf16 v[0:15], v[96:99], v[104:107], v[0:15]
	ds_read_b128 v[96:99], v82 offset:32768
	ds_read_b128 v[100:103], v85 offset:49152
	ds_read_b128 v[104:107], v85 offset:53248
	s_waitcnt lgkmcnt(0)
	v_mfma_f32_32x32x16_bf16 v[48:63], v[96:99], v[100:103], v[48:63]
	v_mfma_f32_32x32x16_bf16 v[32:47], v[96:99], v[104:107], v[32:47]
	ds_read_b128 v[96:99], v82 offset:36864
	s_waitcnt lgkmcnt(0)
	v_mfma_f32_32x32x16_bf16 v[16:31], v[96:99], v[100:103], v[16:31]
	v_mfma_f32_32x32x16_bf16 v[0:15], v[96:99], v[104:107], v[0:15]
	ds_read_b128 v[96:99], v86 offset:32768
	ds_read_b128 v[100:103], v87 offset:49152
	ds_read_b128 v[104:107], v87 offset:53248
	s_waitcnt lgkmcnt(0)
	v_mfma_f32_32x32x16_bf16 v[48:63], v[96:99], v[100:103], v[48:63]
	v_mfma_f32_32x32x16_bf16 v[32:47], v[96:99], v[104:107], v[32:47]
	ds_read_b128 v[96:99], v86 offset:36864
	s_waitcnt vmcnt(0)
	s_waitcnt vmcnt(0) lgkmcnt(0)
	s_barrier
; #define WAIT_V0() asm volatile("s_waitcnt vmcnt(0)" ::: "memory")
; DI void gemm_core(char* smem, int nk, const char* Ab, const char* Bb, const unsigned (&aoff)[4], const unsigned (&boff)[4],
;                   f32x16 (&acc)[2][2]) {
;     ...
;   for (int kt = 0; kt < nk; ++kt) {
;     const int cur = kt & 1;
;     if (kt + 1 < nk) stage(cur ^ 1, kt + 1);
;     const char* sb = smem + cur * STAGE_B;
; #pragma unroll
;     for (int ks = 0; ks < 4; ++ks) {
;       bf16x8 af[2], bfr[2];
; #pragma unroll
;       for (int mb = 0; mb < 2; ++mb) af[mb] = *(const bf16x8*)(sb + a_base + mb * 4096 + xo[ks]);
; #pragma unroll
;       for (int nb = 0; nb < 2; ++nb) bfr[nb] = *(const bf16x8*)(sb + b_base + nb * 4096 + xo[ks]);
; #pragma unroll
;       for (int mb = 0; mb < 2; ++mb)
; #pragma unroll
;         for (int nb = 0; nb < 2; ++nb)
;           acc[mb][nb] = __builtin_amdgcn_mfma_f32_32x32x16_bf16(af[mb], bfr[nb], acc[mb][nb], 0, 0, 0);
;     }
;     WAIT_V0();
;     __syncthreads();
;   }
	v_mfma_f32_32x32x16_bf16 v[16:31], v[96:99], v[100:103], v[16:31]
	v_mfma_f32_32x32x16_bf16 v[0:15], v[96:99], v[104:107], v[0:15]
	v_lshl_add_u64 v[96:97], v[64:65], 0, s[4:5]
	global_load_lds_dwordx4 v[96:97], off
	s_mov_b32 m0, s85
	s_nop 0
	global_load_lds_dwordx4 v76, s[58:59]
	s_mov_b32 m0, s86
	s_nop 0
	global_load_lds_dwordx4 v[88:89], off
	s_mov_b32 m0, s87
	v_lshl_add_u64 v[88:89], v[68:69], 0, s[4:5]
	global_load_lds_dwordx4 v77, s[58:59]
	s_mov_b32 m0, s88
	s_nop 0
	global_load_lds_dwordx4 v[88:89], off
	s_mov_b32 m0, s89
	v_lshl_add_u64 v[88:89], v[70:71], 0, s[4:5]
	global_load_lds_dwordx4 v78, s[58:59]
	s_mov_b32 m0, s90
	s_mov_b64 s[4:5], 0x600
	global_load_lds_dwordx4 v[88:89], off
	s_mov_b32 m0, s91
	s_nop 0
	global_load_lds_dwordx4 v84, s[58:59]
	ds_read_b128 v[88:91], v79
	ds_read_b128 v[92:95], v81 offset:16384
	ds_read_b128 v[96:99], v81 offset:20480
	s_waitcnt lgkmcnt(0)
	v_mfma_f32_32x32x16_bf16 v[48:63], v[88:91], v[92:95], v[48:63]
	s_mov_b32 m0, s18
	v_mfma_f32_32x32x16_bf16 v[32:47], v[88:91], v[96:99], v[32:47]
	ds_read_b128 v[88:91], v79 offset:4096
	s_waitcnt lgkmcnt(0)
	v_mfma_f32_32x32x16_bf16 v[16:31], v[88:91], v[92:95], v[16:31]
	v_mfma_f32_32x32x16_bf16 v[0:15], v[88:91], v[96:99], v[0:15]
	ds_read_b128 v[88:91], v80
	ds_read_b128 v[92:95], v83 offset:16384
	ds_read_b128 v[96:99], v83 offset:20480
	s_waitcnt lgkmcnt(0)
	v_mfma_f32_32x32x16_bf16 v[48:63], v[88:91], v[92:95], v[48:63]
	v_mfma_f32_32x32x16_bf16 v[32:47], v[88:91], v[96:99], v[32:47]
	ds_read_b128 v[88:91], v80 offset:4096
	s_waitcnt lgkmcnt(0)
	v_mfma_f32_32x32x16_bf16 v[16:31], v[88:91], v[92:95], v[16:31]
	v_mfma_f32_32x32x16_bf16 v[0:15], v[88:91], v[96:99], v[0:15]
	ds_read_b128 v[88:91], v82
	ds_read_b128 v[92:95], v85 offset:16384
	ds_read_b128 v[96:99], v85 offset:20480
	s_waitcnt lgkmcnt(0)
	v_mfma_f32_32x32x16_bf16 v[48:63], v[88:91], v[92:95], v[48:63]
	v_mfma_f32_32x32x16_bf16 v[32:47], v[88:91], v[96:99], v[32:47]
	ds_read_b128 v[88:91], v82 offset:4096
	s_waitcnt lgkmcnt(0)
	v_mfma_f32_32x32x16_bf16 v[16:31], v[88:91], v[92:95], v[16:31]
	v_mfma_f32_32x32x16_bf16 v[0:15], v[88:91], v[96:99], v[0:15]
	ds_read_b128 v[88:91], v86
	ds_read_b128 v[92:95], v87 offset:16384
	ds_read_b128 v[96:99], v87 offset:20480
	s_waitcnt lgkmcnt(0)
	v_mfma_f32_32x32x16_bf16 v[48:63], v[88:91], v[92:95], v[48:63]
	v_mfma_f32_32x32x16_bf16 v[32:47], v[88:91], v[96:99], v[32:47]
	ds_read_b128 v[88:91], v86 offset:4096
	s_waitcnt vmcnt(0)
	s_waitcnt vmcnt(0) lgkmcnt(0)
	s_barrier
	v_mfma_f32_32x32x16_bf16 v[16:31], v[88:91], v[92:95], v[16:31]
	v_mfma_f32_32x32x16_bf16 v[0:15], v[88:91], v[96:99], v[0:15]
	v_lshl_add_u64 v[88:89], v[64:65], 0, s[4:5]
	global_load_lds_dwordx4 v[88:89], off
	s_mov_b32 m0, s19
	v_lshl_add_u64 v[88:89], v[66:67], 0, s[4:5]
	global_load_lds_dwordx4 v76, s[60:61]
	s_mov_b32 m0, s22
	s_nop 0
	global_load_lds_dwordx4 v[88:89], off
	s_mov_b32 m0, s23
	v_lshl_add_u64 v[88:89], v[68:69], 0, s[4:5]
	global_load_lds_dwordx4 v77, s[60:61]
	s_mov_b32 m0, s29
	s_nop 0
	global_load_lds_dwordx4 v[88:89], off
	s_mov_b32 m0, s69
	v_lshl_add_u64 v[88:89], v[70:71], 0, s[4:5]
	global_load_lds_dwordx4 v78, s[60:61]
	s_mov_b32 m0, s70
	s_mov_b64 s[4:5], 0x680
	global_load_lds_dwordx4 v[88:89], off
	s_mov_b32 m0, s71
	s_nop 0
	global_load_lds_dwordx4 v84, s[60:61]
	ds_read_b128 v[88:91], v79 offset:32768
	ds_read_b128 v[92:95], v81 offset:49152
	ds_read_b128 v[96:99], v81 offset:53248
	s_waitcnt lgkmcnt(0)
	v_mfma_f32_32x32x16_bf16 v[48:63], v[88:91], v[92:95], v[48:63]
	s_mov_b32 m0, s84
	v_mfma_f32_32x32x16_bf16 v[32:47], v[88:91], v[96:99], v[32:47]
	ds_read_b128 v[88:91], v79 offset:36864
	s_waitcnt lgkmcnt(0)
	v_mfma_f32_32x32x16_bf16 v[16:31], v[88:91], v[92:95], v[16:31]
	v_mfma_f32_32x32x16_bf16 v[0:15], v[88:91], v[96:99], v[0:15]
	ds_read_b128 v[88:91], v80 offset:32768
	ds_read_b128 v[92:95], v83 offset:49152
	ds_read_b128 v[96:99], v83 offset:53248
	s_waitcnt lgkmcnt(0)
	v_mfma_f32_32x32x16_bf16 v[48:63], v[88:91], v[92:95], v[48:63]
	v_mfma_f32_32x32x16_bf16 v[32:47], v[88:91], v[96:99], v[32:47]
	ds_read_b128 v[88:91], v80 offset:36864
	s_waitcnt lgkmcnt(0)
	v_mfma_f32_32x32x16_bf16 v[16:31], v[88:91], v[92:95], v[16:31]
	v_mfma_f32_32x32x16_bf16 v[0:15], v[88:91], v[96:99], v[0:15]
	ds_read_b128 v[88:91], v82 offset:32768
	ds_read_b128 v[92:95], v85 offset:49152
	ds_read_b128 v[96:99], v85 offset:53248
	s_waitcnt lgkmcnt(0)
	v_mfma_f32_32x32x16_bf16 v[48:63], v[88:91], v[92:95], v[48:63]
	v_mfma_f32_32x32x16_bf16 v[32:47], v[88:91], v[96:99], v[32:47]
	ds_read_b128 v[88:91], v82 offset:36864
	s_waitcnt lgkmcnt(0)
	v_mfma_f32_32x32x16_bf16 v[16:31], v[88:91], v[92:95], v[16:31]
	v_mfma_f32_32x32x16_bf16 v[0:15], v[88:91], v[96:99], v[0:15]
	ds_read_b128 v[88:91], v86 offset:32768
	ds_read_b128 v[92:95], v87 offset:49152
	ds_read_b128 v[96:99], v87 offset:53248
	s_waitcnt lgkmcnt(0)
	v_mfma_f32_32x32x16_bf16 v[48:63], v[88:91], v[92:95], v[48:63]
	v_mfma_f32_32x32x16_bf16 v[32:47], v[88:91], v[96:99], v[32:47]
	ds_read_b128 v[88:91], v86 offset:36864
	s_waitcnt vmcnt(0)
	s_waitcnt vmcnt(0) lgkmcnt(0)
	s_barrier
; #define WAIT_V0() asm volatile("s_waitcnt vmcnt(0)" ::: "memory")
; DI void gemm_core(char* smem, int nk, const char* Ab, const char* Bb, const unsigned (&aoff)[4], const unsigned (&boff)[4],
;                   f32x16 (&acc)[2][2]) {
;     ...
;   for (int kt = 0; kt < nk; ++kt) {
;     const int cur = kt & 1;
;     if (kt + 1 < nk) stage(cur ^ 1, kt + 1);
;     const char* sb = smem + cur * STAGE_B;
; #pragma unroll
;     for (int ks = 0; ks < 4; ++ks) {
;       bf16x8 af[2], bfr[2];
; #pragma unroll
;       for (int mb = 0; mb < 2; ++mb) af[mb] = *(const bf16x8*)(sb + a_base + mb * 4096 + xo[ks]);
; #pragma unroll
;       for (int nb = 0; nb < 2; ++nb) bfr[nb] = *(const bf16x8*)(sb + b_base + nb * 4096 + xo[ks]);
; #pragma unroll
;       for (int mb = 0; mb < 2; ++mb)
; #pragma unroll
;         for (int nb = 0; nb < 2; ++nb)
;           acc[mb][nb] = __builtin_amdgcn_mfma_f32_32x32x16_bf16(af[mb], bfr[nb], acc[mb][nb], 0, 0, 0);
;     }
;     WAIT_V0();
;     __syncthreads();
;   }
	v_mfma_f32_32x32x16_bf16 v[16:31], v[88:91], v[92:95], v[16:31]
	v_mfma_f32_32x32x16_bf16 v[0:15], v[88:91], v[96:99], v[0:15]
	v_lshl_add_u64 v[88:89], v[64:65], 0, s[4:5]
	global_load_lds_dwordx4 v[88:89], off
	s_mov_b32 m0, s85
	v_lshl_add_u64 v[88:89], v[66:67], 0, s[4:5]
	global_load_lds_dwordx4 v76, s[62:63]
	s_mov_b32 m0, s86
	s_nop 0
	global_load_lds_dwordx4 v[88:89], off
	s_mov_b32 m0, s87
	v_lshl_add_u64 v[88:89], v[68:69], 0, s[4:5]
	global_load_lds_dwordx4 v77, s[62:63]
	s_mov_b32 m0, s88
	s_nop 0
	global_load_lds_dwordx4 v[88:89], off
	s_mov_b32 m0, s89
	v_lshl_add_u64 v[88:89], v[70:71], 0, s[4:5]
	global_load_lds_dwordx4 v78, s[62:63]
	s_mov_b32 m0, s90
	s_mov_b64 s[4:5], 0x700
	global_load_lds_dwordx4 v[88:89], off
	s_mov_b32 m0, s91
	s_nop 0
	global_load_lds_dwordx4 v84, s[62:63]
	ds_read_b128 v[88:91], v79
	ds_read_b128 v[92:95], v81 offset:16384
	ds_read_b128 v[96:99], v81 offset:20480
	s_waitcnt lgkmcnt(0)
	v_mfma_f32_32x32x16_bf16 v[48:63], v[88:91], v[92:95], v[48:63]
	s_mov_b32 m0, s18
	v_mfma_f32_32x32x16_bf16 v[32:47], v[88:91], v[96:99], v[32:47]
	ds_read_b128 v[88:91], v79 offset:4096
	s_waitcnt lgkmcnt(0)
	v_mfma_f32_32x32x16_bf16 v[16:31], v[88:91], v[92:95], v[16:31]
	v_mfma_f32_32x32x16_bf16 v[0:15], v[88:91], v[96:99], v[0:15]
	ds_read_b128 v[88:91], v80
	ds_read_b128 v[92:95], v83 offset:16384
	ds_read_b128 v[96:99], v83 offset:20480
	s_waitcnt lgkmcnt(0)
	v_mfma_f32_32x32x16_bf16 v[48:63], v[88:91], v[92:95], v[48:63]
	v_mfma_f32_32x32x16_bf16 v[32:47], v[88:91], v[96:99], v[32:47]
	ds_read_b128 v[88:91], v80 offset:4096
	s_waitcnt lgkmcnt(0)
	v_mfma_f32_32x32x16_bf16 v[16:31], v[88:91], v[92:95], v[16:31]
	v_mfma_f32_32x32x16_bf16 v[0:15], v[88:91], v[96:99], v[0:15]
	ds_read_b128 v[88:91], v82
	ds_read_b128 v[92:95], v85 offset:16384
	ds_read_b128 v[96:99], v85 offset:20480
	s_waitcnt lgkmcnt(0)
	v_mfma_f32_32x32x16_bf16 v[48:63], v[88:91], v[92:95], v[48:63]
	v_mfma_f32_32x32x16_bf16 v[32:47], v[88:91], v[96:99], v[32:47]
	ds_read_b128 v[88:91], v82 offset:4096
	s_waitcnt lgkmcnt(0)
	v_mfma_f32_32x32x16_bf16 v[16:31], v[88:91], v[92:95], v[16:31]
	v_mfma_f32_32x32x16_bf16 v[0:15], v[88:91], v[96:99], v[0:15]
	ds_read_b128 v[88:91], v86
	ds_read_b128 v[92:95], v87 offset:16384
	ds_read_b128 v[96:99], v87 offset:20480
	s_waitcnt lgkmcnt(0)
	v_mfma_f32_32x32x16_bf16 v[48:63], v[88:91], v[92:95], v[48:63]
	v_mfma_f32_32x32x16_bf16 v[32:47], v[88:91], v[96:99], v[32:47]
	ds_read_b128 v[88:91], v86 offset:4096
	s_waitcnt vmcnt(0)
	s_waitcnt vmcnt(0) lgkmcnt(0)
	s_barrier
	v_mfma_f32_32x32x16_bf16 v[16:31], v[88:91], v[92:95], v[16:31]
	v_mfma_f32_32x32x16_bf16 v[0:15], v[88:91], v[96:99], v[0:15]
	v_lshl_add_u64 v[88:89], v[64:65], 0, s[4:5]
	global_load_lds_dwordx4 v[88:89], off
	s_mov_b32 m0, s19
	v_lshl_add_u64 v[88:89], v[66:67], 0, s[4:5]
	global_load_lds_dwordx4 v76, s[64:65]
	s_mov_b32 m0, s22
	s_nop 0
	global_load_lds_dwordx4 v[88:89], off
	s_mov_b32 m0, s23
	v_lshl_add_u64 v[88:89], v[68:69], 0, s[4:5]
	global_load_lds_dwordx4 v77, s[64:65]
	s_mov_b32 m0, s29
	s_nop 0
	global_load_lds_dwordx4 v[88:89], off
	s_mov_b32 m0, s69
	v_lshl_add_u64 v[88:89], v[70:71], 0, s[4:5]
	global_load_lds_dwordx4 v78, s[64:65]
	s_mov_b32 m0, s70
	s_mov_b64 s[4:5], 0x780
	global_load_lds_dwordx4 v[88:89], off
	s_mov_b32 m0, s71
	v_lshl_add_u64 v[64:65], v[64:65], 0, s[4:5]
	global_load_lds_dwordx4 v84, s[64:65]
	ds_read_b128 v[88:91], v79 offset:32768
	ds_read_b128 v[92:95], v81 offset:49152
	ds_read_b128 v[96:99], v81 offset:53248
	s_waitcnt lgkmcnt(0)
	v_mfma_f32_32x32x16_bf16 v[48:63], v[88:91], v[92:95], v[48:63]
	s_mov_b32 m0, s84
	s_movk_i32 s4, 0x4000
	v_mfma_f32_32x32x16_bf16 v[32:47], v[88:91], v[96:99], v[32:47]
	ds_read_b128 v[88:91], v79 offset:36864
	s_waitcnt lgkmcnt(0)
	v_mfma_f32_32x32x16_bf16 v[16:31], v[88:91], v[92:95], v[16:31]
	v_mfma_f32_32x32x16_bf16 v[0:15], v[88:91], v[96:99], v[0:15]
	ds_read_b128 v[88:91], v80 offset:32768
	ds_read_b128 v[92:95], v83 offset:49152
	ds_read_b128 v[96:99], v83 offset:53248
	s_waitcnt lgkmcnt(0)
	v_mfma_f32_32x32x16_bf16 v[48:63], v[88:91], v[92:95], v[48:63]
	v_mfma_f32_32x32x16_bf16 v[32:47], v[88:91], v[96:99], v[32:47]
	ds_read_b128 v[88:91], v80 offset:36864
	s_waitcnt lgkmcnt(0)
	v_mfma_f32_32x32x16_bf16 v[16:31], v[88:91], v[92:95], v[16:31]
	v_mfma_f32_32x32x16_bf16 v[0:15], v[88:91], v[96:99], v[0:15]
	ds_read_b128 v[88:91], v82 offset:32768
	ds_read_b128 v[92:95], v85 offset:49152
	ds_read_b128 v[96:99], v85 offset:53248
	s_waitcnt lgkmcnt(0)
	v_mfma_f32_32x32x16_bf16 v[48:63], v[88:91], v[92:95], v[48:63]
	v_mfma_f32_32x32x16_bf16 v[32:47], v[88:91], v[96:99], v[32:47]
	ds_read_b128 v[88:91], v82 offset:36864
	s_waitcnt lgkmcnt(0)
	v_mfma_f32_32x32x16_bf16 v[16:31], v[88:91], v[92:95], v[16:31]
	v_mfma_f32_32x32x16_bf16 v[0:15], v[88:91], v[96:99], v[0:15]
	ds_read_b128 v[88:91], v86 offset:32768
	ds_read_b128 v[92:95], v87 offset:49152
	ds_read_b128 v[96:99], v87 offset:53248
	s_waitcnt lgkmcnt(0)
	v_mfma_f32_32x32x16_bf16 v[48:63], v[88:91], v[92:95], v[48:63]
	v_mfma_f32_32x32x16_bf16 v[32:47], v[88:91], v[96:99], v[32:47]
	ds_read_b128 v[88:91], v86 offset:36864
	s_waitcnt vmcnt(0)
	s_waitcnt vmcnt(0) lgkmcnt(0)
	s_barrier
; #define WAIT_V0() asm volatile("s_waitcnt vmcnt(0)" ::: "memory")
; DI void gemm_core(char* smem, int nk, const char* Ab, const char* Bb, const unsigned (&aoff)[4], const unsigned (&boff)[4],
;                   f32x16 (&acc)[2][2]) {
;     ...
;   for (int kt = 0; kt < nk; ++kt) {
;     const int cur = kt & 1;
;     if (kt + 1 < nk) stage(cur ^ 1, kt + 1);
;     const char* sb = smem + cur * STAGE_B;
; #pragma unroll
;     for (int ks = 0; ks < 4; ++ks) {
;       bf16x8 af[2], bfr[2];
; #pragma unroll
;       for (int mb = 0; mb < 2; ++mb) af[mb] = *(const bf16x8*)(sb + a_base + mb * 4096 + xo[ks]);
; #pragma unroll
;       for (int nb = 0; nb < 2; ++nb) bfr[nb] = *(const bf16x8*)(sb + b_base + nb * 4096 + xo[ks]);
; #pragma unroll
;       for (int mb = 0; mb < 2; ++mb)
; #pragma unroll
;         for (int nb = 0; nb < 2; ++nb)
;           acc[mb][nb] = __builtin_amdgcn_mfma_f32_32x32x16_bf16(af[mb], bfr[nb], acc[mb][nb], 0, 0, 0);
;     }
;     WAIT_V0();
;     __syncthreads();
;   }
	global_load_lds_dwordx4 v[64:65], off
	s_mov_b32 m0, s85
	v_lshl_add_u64 v[64:65], v[66:67], 0, s[6:7]
	global_load_lds_dwordx4 v76, s[66:67]
	s_mov_b32 m0, s86
	v_mfma_f32_32x32x16_bf16 v[16:31], v[88:91], v[92:95], v[16:31]
	global_load_lds_dwordx4 v[64:65], off
	s_mov_b32 m0, s87
	v_lshl_add_u64 v[64:65], v[68:69], 0, s[6:7]
	global_load_lds_dwordx4 v77, s[66:67]
	s_mov_b32 m0, s88
	v_mfma_f32_32x32x16_bf16 v[0:15], v[88:91], v[96:99], v[0:15]
	global_load_lds_dwordx4 v[64:65], off
	s_mov_b32 m0, s89
	v_lshl_add_u64 v[64:65], v[70:71], 0, s[6:7]
	global_load_lds_dwordx4 v78, s[66:67]
	s_mov_b32 m0, s90
	v_readlane_b32 s86, v254, 58
	global_load_lds_dwordx4 v[64:65], off
	s_mov_b32 m0, s91
	v_readlane_b32 s87, v254, 59
	global_load_lds_dwordx4 v84, s[66:67]
	ds_read_b128 v[64:67], v79
	ds_read_b128 v[68:71], v81 offset:16384
	ds_read_b128 v[88:91], v81 offset:20480
	s_waitcnt lgkmcnt(0)
	v_mfma_f32_32x32x16_bf16 v[48:63], v[64:67], v[68:71], v[48:63]
	v_mfma_f32_32x32x16_bf16 v[32:47], v[64:67], v[88:91], v[32:47]
	ds_read_b128 v[64:67], v79 offset:4096
	s_waitcnt lgkmcnt(0)
	v_mfma_f32_32x32x16_bf16 v[16:31], v[64:67], v[68:71], v[16:31]
	v_mfma_f32_32x32x16_bf16 v[0:15], v[64:67], v[88:91], v[0:15]
	ds_read_b128 v[64:67], v80
	ds_read_b128 v[68:71], v83 offset:16384
	ds_read_b128 v[88:91], v83 offset:20480
	s_waitcnt lgkmcnt(0)
	v_mfma_f32_32x32x16_bf16 v[48:63], v[64:67], v[68:71], v[48:63]
	v_mfma_f32_32x32x16_bf16 v[32:47], v[64:67], v[88:91], v[32:47]
	ds_read_b128 v[64:67], v80 offset:4096
	s_waitcnt lgkmcnt(0)
	v_mfma_f32_32x32x16_bf16 v[16:31], v[64:67], v[68:71], v[16:31]
	v_mfma_f32_32x32x16_bf16 v[0:15], v[64:67], v[88:91], v[0:15]
	ds_read_b128 v[64:67], v82
	ds_read_b128 v[68:71], v85 offset:16384
	ds_read_b128 v[88:91], v85 offset:20480
	s_waitcnt lgkmcnt(0)
	v_mfma_f32_32x32x16_bf16 v[48:63], v[64:67], v[68:71], v[48:63]
	v_mfma_f32_32x32x16_bf16 v[32:47], v[64:67], v[88:91], v[32:47]
	ds_read_b128 v[64:67], v82 offset:4096
	s_waitcnt lgkmcnt(0)
	v_mfma_f32_32x32x16_bf16 v[16:31], v[64:67], v[68:71], v[16:31]
	v_mfma_f32_32x32x16_bf16 v[0:15], v[64:67], v[88:91], v[0:15]
	ds_read_b128 v[64:67], v86
	ds_read_b128 v[68:71], v87 offset:16384
	ds_read_b128 v[88:91], v87 offset:20480
	s_waitcnt lgkmcnt(0)
	v_mfma_f32_32x32x16_bf16 v[48:63], v[64:67], v[68:71], v[48:63]
	v_mfma_f32_32x32x16_bf16 v[32:47], v[64:67], v[88:91], v[32:47]
	ds_read_b128 v[64:67], v86 offset:4096
	s_waitcnt vmcnt(0)
	s_waitcnt vmcnt(0) lgkmcnt(0)
	s_barrier
	v_mfma_f32_32x32x16_bf16 v[16:31], v[64:67], v[68:71], v[16:31]
	v_mfma_f32_32x32x16_bf16 v[0:15], v[64:67], v[88:91], v[0:15]
	ds_read_b128 v[64:67], v79 offset:32768
	ds_read_b128 v[68:71], v81 offset:49152
	ds_read_b128 v[88:91], v81 offset:53248
	s_waitcnt lgkmcnt(1)
	v_mfma_f32_32x32x16_bf16 v[48:63], v[64:67], v[68:71], v[48:63]
	s_waitcnt lgkmcnt(0)
	v_mfma_f32_32x32x16_bf16 v[32:47], v[64:67], v[88:91], v[32:47]
	ds_read_b128 v[64:67], v79 offset:36864
	s_waitcnt lgkmcnt(0)
	v_mfma_f32_32x32x16_bf16 v[16:31], v[64:67], v[68:71], v[16:31]
	v_mfma_f32_32x32x16_bf16 v[0:15], v[64:67], v[88:91], v[0:15]
	ds_read_b128 v[64:67], v80 offset:32768
	ds_read_b128 v[68:71], v83 offset:49152
	ds_read_b128 v[76:79], v83 offset:53248
	s_waitcnt lgkmcnt(1)
	v_mfma_f32_32x32x16_bf16 v[48:63], v[64:67], v[68:71], v[48:63]
	s_waitcnt lgkmcnt(0)
	v_mfma_f32_32x32x16_bf16 v[32:47], v[64:67], v[76:79], v[32:47]
	ds_read_b128 v[64:67], v80 offset:36864
	s_waitcnt lgkmcnt(0)
	v_mfma_f32_32x32x16_bf16 v[16:31], v[64:67], v[68:71], v[16:31]
	v_mfma_f32_32x32x16_bf16 v[0:15], v[64:67], v[76:79], v[0:15]
	ds_read_b128 v[64:67], v82 offset:32768
	ds_read_b128 v[68:71], v85 offset:49152
	ds_read_b128 v[76:79], v85 offset:53248
	s_waitcnt lgkmcnt(1)
	v_mfma_f32_32x32x16_bf16 v[48:63], v[64:67], v[68:71], v[48:63]
	s_waitcnt lgkmcnt(0)
	v_mfma_f32_32x32x16_bf16 v[32:47], v[64:67], v[76:79], v[32:47]
	ds_read_b128 v[64:67], v82 offset:36864
	s_waitcnt lgkmcnt(0)
	v_mfma_f32_32x32x16_bf16 v[16:31], v[64:67], v[68:71], v[16:31]
	ds_read_b128 v[68:71], v87 offset:53248
	ds_read_b128 v[80:83], v87 offset:49152
	ds_read_b128 v[88:91], v86 offset:36864
	ds_read_b128 v[84:87], v86 offset:32768
	s_waitcnt vmcnt(0)
	s_waitcnt lgkmcnt(0)
	s_barrier
; template <class F>
; DI void epi_foreach(const f32x16 (&acc)[2][2], F f) {
;     ...
;   for (int mb = 0; mb < 2; ++mb)
; #pragma unroll
;     for (int nb = 0; nb < 2; ++nb)
; #pragma unroll
;       for (int r = 0; r < 16; ++r) {
;         const int row = wm * 64 + mb * 32 + (r & 3) + 8 * (r >> 2) + 4 * (lane >> 5);
;         const int col = wn * 64 + nb * 32 + (lane & 31);
;         f(row, col, acc[mb][nb][r]);
;         if ((r & 7) == 7) __builtin_amdgcn_sched_barrier(0);
; DI void phase_up(const Params& P, int layer, char* smem) {
;     ...
;     f32x16 acc[2][2];
;     gemm_core(smem, 16, Abase, (const char*)wup, aoff, boff, acc);
;     epi_foreach(acc, [&](int row, int col, float v) __attribute__((always_inline)) { Cs[row * 136 + col] = f2bf(v); });
;     __syncthreads();
;     {
;       const int col = tid & 63, rb = tid >> 6;
;       const int cv = nt * 64 + col, cg_ = DFF + nt * 64 + col;
;       const float w0v = cw[cv], w1v = cw[5632 + cv], w2v = cw[2 * 5632 + cv], bv = cb[cv];
;       const float w0g = cw[cg_], w1g = cw[5632 + cg_], w2g = cw[2 * 5632 + cg_], bgt = cb[cg_];
	v_mfma_f32_32x32x16_bf16 v[48:63], v[84:87], v[80:83], v[48:63]
	v_mfma_f32_32x32x16_bf16 v[0:15], v[64:67], v[76:79], v[0:15]
	v_mov_b32_e32 v64, v161
	v_mov_b32_e32 v65, v161
	v_lshrrev_b32_e32 v67, 3, v64
	v_and_b32_e32 v67, 4, v67
	v_lshrrev_b32_e32 v66, 1, v65
	v_and_b32_e32 v64, 31, v64
	v_and_or_b32 v64, v65, 64, v64
	v_and_or_b32 v65, v66, s3, v67
	v_mul_lo_u32 v65, v65, s97
	s_nop 1
	v_cvt_pk_bf16_f32 v48, v48, s0
	v_lshl_add_u32 v64, v64, 1, v65
	ds_write_b16 v64, v48
	v_cvt_pk_bf16_f32 v48, v49, s0
	ds_write_b16 v64, v48 offset:272
	v_cvt_pk_bf16_f32 v48, v50, s0
	ds_write_b16 v64, v48 offset:544
	v_cvt_pk_bf16_f32 v48, v51, s0
	ds_write_b16 v64, v48 offset:816
	v_cvt_pk_bf16_f32 v48, v52, s0
	ds_write_b16 v64, v48 offset:2176
	v_cvt_pk_bf16_f32 v48, v53, s0
	ds_write_b16 v64, v48 offset:2448
	v_cvt_pk_bf16_f32 v48, v54, s0
	ds_write_b16 v64, v48 offset:2720
	v_cvt_pk_bf16_f32 v48, v55, s0
	v_mfma_f32_32x32x16_bf16 v[32:47], v[84:87], v[68:71], v[32:47]
	ds_write_b16 v64, v48 offset:2992
	v_mfma_f32_32x32x16_bf16 v[16:31], v[88:91], v[80:83], v[16:31]
	v_mfma_f32_32x32x16_bf16 v[0:15], v[88:91], v[68:71], v[0:15]
	v_cvt_pk_bf16_f32 v48, v56, s0
	ds_write_b16 v64, v48 offset:4352
	v_cvt_pk_bf16_f32 v48, v57, s0
	ds_write_b16 v64, v48 offset:4624
	v_cvt_pk_bf16_f32 v48, v58, s0
	ds_write_b16 v64, v48 offset:4896
	v_cvt_pk_bf16_f32 v48, v59, s0
	ds_write_b16 v64, v48 offset:5168
	v_cvt_pk_bf16_f32 v48, v60, s0
	ds_write_b16 v64, v48 offset:6528
	v_cvt_pk_bf16_f32 v48, v61, s0
	ds_write_b16 v64, v48 offset:6800
	v_cvt_pk_bf16_f32 v48, v62, s0
	ds_write_b16 v64, v48 offset:7072
	v_cvt_pk_bf16_f32 v48, v63, s0
	ds_write_b16 v64, v48 offset:7344
	v_cvt_pk_bf16_f32 v32, v32, s0
	ds_write_b16 v64, v32 offset:64
	v_cvt_pk_bf16_f32 v32, v33, s0
	ds_write_b16 v64, v32 offset:336
	v_cvt_pk_bf16_f32 v32, v34, s0
	ds_write_b16 v64, v32 offset:608
	v_cvt_pk_bf16_f32 v32, v35, s0
	ds_write_b16 v64, v32 offset:880
	v_cvt_pk_bf16_f32 v32, v36, s0
	ds_write_b16 v64, v32 offset:2240
	v_cvt_pk_bf16_f32 v32, v37, s0
	ds_write_b16 v64, v32 offset:2512
	v_cvt_pk_bf16_f32 v32, v38, s0
	ds_write_b16 v64, v32 offset:2784
	v_cvt_pk_bf16_f32 v32, v39, s0
	ds_write_b16 v64, v32 offset:3056
	v_cvt_pk_bf16_f32 v32, v40, s0
	ds_write_b16 v64, v32 offset:4416
	v_cvt_pk_bf16_f32 v32, v41, s0
	ds_write_b16 v64, v32 offset:4688
	v_cvt_pk_bf16_f32 v32, v42, s0
	ds_write_b16 v64, v32 offset:4960
	v_cvt_pk_bf16_f32 v32, v43, s0
	ds_write_b16 v64, v32 offset:5232
	v_cvt_pk_bf16_f32 v32, v44, s0
	ds_write_b16 v64, v32 offset:6592
	v_cvt_pk_bf16_f32 v32, v45, s0
	ds_write_b16 v64, v32 offset:6864
	v_cvt_pk_bf16_f32 v32, v46, s0
	ds_write_b16 v64, v32 offset:7136
	v_cvt_pk_bf16_f32 v32, v47, s0
	ds_write_b16 v64, v32 offset:7408
	v_cvt_pk_bf16_f32 v16, v16, s0
	ds_write_b16 v64, v16 offset:8704
	v_cvt_pk_bf16_f32 v16, v17, s0
	ds_write_b16 v64, v16 offset:8976
	v_cvt_pk_bf16_f32 v16, v18, s0
	ds_write_b16 v64, v16 offset:9248
	v_cvt_pk_bf16_f32 v16, v19, s0
	ds_write_b16 v64, v16 offset:9520
	v_cvt_pk_bf16_f32 v16, v20, s0
	ds_write_b16 v64, v16 offset:10880
	v_cvt_pk_bf16_f32 v16, v21, s0
	ds_write_b16 v64, v16 offset:11152
	v_cvt_pk_bf16_f32 v16, v22, s0
	ds_write_b16 v64, v16 offset:11424
	v_cvt_pk_bf16_f32 v16, v23, s0
	ds_write_b16 v64, v16 offset:11696
	v_cvt_pk_bf16_f32 v16, v24, s0
	ds_write_b16 v64, v16 offset:13056
	v_cvt_pk_bf16_f32 v16, v25, s0
	ds_write_b16 v64, v16 offset:13328
	v_cvt_pk_bf16_f32 v16, v26, s0
	ds_write_b16 v64, v16 offset:13600
	v_cvt_pk_bf16_f32 v16, v27, s0
	ds_write_b16 v64, v16 offset:13872
	v_cvt_pk_bf16_f32 v16, v28, s0
	ds_write_b16 v64, v16 offset:15232
	v_cvt_pk_bf16_f32 v16, v29, s0
	ds_write_b16 v64, v16 offset:15504
	v_cvt_pk_bf16_f32 v16, v30, s0
	ds_write_b16 v64, v16 offset:15776
	v_cvt_pk_bf16_f32 v16, v31, s0
	ds_write_b16 v64, v16 offset:16048
	v_cvt_pk_bf16_f32 v0, v0, s0
	ds_write_b16 v64, v0 offset:8768
	v_cvt_pk_bf16_f32 v0, v1, s0
	ds_write_b16 v64, v0 offset:9040
	v_cvt_pk_bf16_f32 v0, v2, s0
	ds_write_b16 v64, v0 offset:9312
	v_cvt_pk_bf16_f32 v0, v3, s0
	ds_write_b16 v64, v0 offset:9584
	v_cvt_pk_bf16_f32 v0, v4, s0
	ds_write_b16 v64, v0 offset:10944
	v_cvt_pk_bf16_f32 v0, v5, s0
	ds_write_b16 v64, v0 offset:11216
	v_cvt_pk_bf16_f32 v0, v6, s0
	ds_write_b16 v64, v0 offset:11488
	v_cvt_pk_bf16_f32 v0, v7, s0
	ds_write_b16 v64, v0 offset:11760
	v_cvt_pk_bf16_f32 v0, v8, s0
	ds_write_b16 v64, v0 offset:13120
	v_cvt_pk_bf16_f32 v0, v9, s0
	ds_write_b16 v64, v0 offset:13392
	v_cvt_pk_bf16_f32 v0, v10, s0
	ds_write_b16 v64, v0 offset:13664
	v_cvt_pk_bf16_f32 v0, v11, s0
	ds_write_b16 v64, v0 offset:13936
	v_cvt_pk_bf16_f32 v0, v12, s0
	ds_write_b16 v64, v0 offset:15296
	v_cvt_pk_bf16_f32 v0, v13, s0
	ds_write_b16 v64, v0 offset:15568
	v_cvt_pk_bf16_f32 v0, v14, s0
	ds_write_b16 v64, v0 offset:15840
	v_cvt_pk_bf16_f32 v0, v15, s0
	ds_write_b16 v64, v0 offset:16112
	s_waitcnt lgkmcnt(0)
	s_barrier
	s_and_saveexec_b64 s[18:19], s[40:41]
	s_mov_b32 s3, 0xb000
	s_cbranch_execz .LBB0_24
	v_add_u32_e32 v136, s21, v74
	v_lshlrev_b64 v[4:5], 2, v[136:137]
	v_lshl_add_u64 v[8:9], s[10:11], 0, v[4:5]
	v_or_b32_e32 v10, s21, v72
	v_lshl_add_u64 v[2:3], s[12:13], 0, v[4:5]
	v_add_co_u32_e32 v4, vcc, 0xb000, v8
	v_ashrrev_i32_e32 v11, 31, v10
	s_nop 0
	v_addc_co_u32_e32 v5, vcc, 0, v9, vcc
	v_lshl_add_u64 v[0:1], v[10:11], 1, s[86:87]
	v_add_co_u32_e32 v6, vcc, 0x5000, v8
	v_lshlrev_b64 v[10:11], 2, v[10:11]
	s_nop 0
	v_addc_co_u32_e32 v7, vcc, 0, v9, vcc
	v_lshl_add_u64 v[12:13], s[12:13], 0, v[10:11]
	v_lshl_add_u64 v[10:11], s[10:11], 0, v[10:11]
	global_load_dword v3, v[2:3], off
	s_mulk_i32 s20, 0x7e
	global_load_dword v5, v[4:5], off
	s_nop 0
	global_load_dword v7, v[6:7], off offset:2048
	s_nop 0
	global_load_dword v9, v[8:9], off
	s_mul_i32 s21, s68, 0x7a
	global_load_dword v2, v[12:13], off
	v_add_co_u32_e32 v12, vcc, s3, v10
	s_sub_i32 s29, s20, s21
	s_nop 0
	v_addc_co_u32_e32 v13, vcc, 0, v11, vcc
	global_load_dword v4, v[12:13], off
	v_add_co_u32_e32 v12, vcc, 0x5000, v10
	s_mov_b64 s[20:21], 0
	s_nop 0
	v_addc_co_u32_e32 v13, vcc, 0, v11, vcc
	global_load_dword v6, v[12:13], off offset:2048
	global_load_dword v8, v[10:11], off
	v_mov_b32_e32 v11, v73
	v_mov_b32_e32 v10, v75
	s_waitcnt vmcnt(0)
	v_readfirstlane_b32 s22, v73
	s_branch .LBB0_28
; DI float bf2f(unsigned short u) { return __uint_as_float(((unsigned)u) << 16); }
; DI void phase_up(const Params& P, int layer, char* smem) {
;     ...
;       for (int r = 2 + rb; r < 128; r += 4) {
;         const int tb = tb0 + r;
;         if (tb < S_) {
;           const float val = bv + w0v * bf2f(Cs[(r - 2) * 136 + col]) + w1v * bf2f(Cs[(r - 1) * 136 + col]) + w2v * bf2f(Cs[r * 136 + col]);
;           const float gat = bgt + w0g * bf2f(Cs[(r - 2) * 136 + 64 + col]) + w1g * bf2f(Cs[(r - 1) * 136 + 64 + col]) + w2g * bf2f(Cs[r * 136 + 64 + col]);
;           const float a = gat / (1.f + __expf(-gat)) * val;
;           ACT[(size_t)(b * S_ + tb) * DFF + cv] = f2bf(a);
;         }
;       }
.LBB0_28:
	ds_read_u16 v12, v10
	ds_read_u16 v13, v10 offset:128
	ds_read_u16 v14, v10 offset:272
	ds_read_u16 v15, v10 offset:400
	ds_read_u16 v16, v10 offset:544
	ds_read_u16 v17, v10 offset:672
	ds_read_u16 v118, v10 offset:1088
	ds_read_u16 v119, v10 offset:1216
	ds_read_u16 v120, v10 offset:1360
	ds_read_u16 v121, v10 offset:1488
	ds_read_u16 v122, v10 offset:1632
	ds_read_u16 v123, v10 offset:1760
	s_waitcnt lgkmcnt(10)
	v_lshlrev_b32_e32 v13, 16, v13
	v_lshlrev_b32_e32 v12, 16, v12
	v_pk_fma_f32 v[12:13], v[8:9], v[12:13], v[2:3]
	s_waitcnt lgkmcnt(8)
	v_lshlrev_b32_e32 v15, 16, v15
	v_lshlrev_b32_e32 v14, 16, v14
	v_pk_fma_f32 v[12:13], v[6:7], v[14:15], v[12:13]
	s_waitcnt lgkmcnt(6)
	v_lshlrev_b32_e32 v15, 16, v17
	v_lshlrev_b32_e32 v14, 16, v16
	v_pk_fma_f32 v[12:13], v[4:5], v[14:15], v[12:13]
	s_waitcnt lgkmcnt(4)
	v_lshlrev_b32_e32 v119, 16, v119
	v_lshlrev_b32_e32 v118, 16, v118
	v_mul_f32_e32 v14, 0xbfb8aa3b, v13
	v_pk_fma_f32 v[118:119], v[8:9], v[118:119], v[2:3]
	v_exp_f32_e32 v14, v14
	s_waitcnt lgkmcnt(2)
	v_lshlrev_b32_e32 v121, 16, v121
	v_lshlrev_b32_e32 v120, 16, v120
	v_add_f32_e32 v14, 1.0, v14
	v_pk_fma_f32 v[118:119], v[6:7], v[120:121], v[118:119]
	v_div_scale_f32 v15, s[68:69], v14, v14, v13
	s_waitcnt lgkmcnt(0)
	v_lshlrev_b32_e32 v121, 16, v123
	v_lshlrev_b32_e32 v120, 16, v122
	v_rcp_f32_e32 v16, v15
	v_pk_fma_f32 v[118:119], v[4:5], v[120:121], v[118:119]
	v_fma_f32 v17, -v15, v16, 1.0
	v_mul_f32_e32 v120, 0xbfb8aa3b, v119
	v_fmac_f32_e32 v16, v17, v16
	v_exp_f32_e32 v120, v120
	v_div_scale_f32 v17, vcc, v13, v14, v13
	v_add_f32_e32 v120, 1.0, v120
	v_mul_f32_e32 v18, v17, v16
	v_div_scale_f32 v121, s[68:69], v120, v120, v119
	v_fma_f32 v19, -v15, v18, v17
	v_rcp_f32_e32 v122, v121
	v_fmac_f32_e32 v18, v19, v16
	v_fma_f32 v15, -v15, v18, v17
	v_fma_f32 v123, -v121, v122, 1.0
	v_div_fmas_f32 v15, v15, v16, v18
	v_fmac_f32_e32 v122, v123, v122
	v_div_fixup_f32 v13, v15, v14, v13
	v_div_scale_f32 v123, vcc, v119, v120, v119
	v_mul_f32_e32 v12, v12, v13
	v_mul_f32_e32 v124, v123, v122
	v_cvt_pk_bf16_f32 v14, v12, s0
	v_fma_f32 v125, -v121, v124, v123
	v_fmac_f32_e32 v124, v125, v122
	v_fma_f32 v121, -v121, v124, v123
	v_div_fmas_f32 v121, v121, v122, v124
	v_div_fixup_f32 v119, v121, v120, v119
	v_mul_f32_e32 v118, v118, v119
	v_cvt_pk_bf16_f32 v120, v118, s0
	s_add_i32 s23, s28, s22
	s_cmp_lt_i32 s23, s4
	s_cbranch_scc0 .Lconv_skipA
	v_add_u32_e32 v12, s29, v11
	v_mad_i64_i32 v[12:13], s[68:69], v12, s33, v[0:1]
	global_store_short v[12:13], v14, off
.Lconv_skipA:
	s_add_i32 s23, s22, 4
	s_cmpk_gt_i32 s23, 0x7d
	s_cbranch_scc1 .Lconv_skipB
	s_add_i32 s23, s23, s28
	s_cmp_lt_i32 s23, s4
	s_cbranch_scc0 .Lconv_skipB
	v_add_u32_e32 v118, s29, v11
	v_add_u32_e32 v118, 4, v118
	v_mad_i64_i32 v[118:119], s[68:69], v118, s33, v[0:1]
	global_store_short v[118:119], v120, off
.Lconv_skipB:
	s_add_i32 s22, s22, 8
	v_add_u32_e32 v11, 8, v11
	v_add_u32_e32 v10, 0x880, v10
	s_cmpk_gt_i32 s22, 0x7d
	s_cbranch_scc0 .LBB0_28
	s_branch .LBB0_24
